# qk_prep next-token L2 touch + DPP/permlane reductions, GateUp conv shuffles via DPP row_ror
# speedup vs baseline: 1.0082x; 1.0028x over previous
; __device__ __forceinline__ int opaque_tid() { int t = threadIdx.x; asm volatile("" : "+v"(t)); return t; }
; __device__ __forceinline__ float bf2f(unsigned short h) { return __uint_as_float(((unsigned)h) << 16); }
; __device__ __forceinline__ void pass_qk_prep(const Params& P) {
;     const int tidx = opaque_tid();
;     const int lane = tidx & 63;
;     bf16_t* QB = (bf16_t*)(P.ws + WS_QB); const bf16_t* KVR = (const bf16_t*)(P.ws + WS_KVR); const bf16_t* ZB = (const bf16_t*)(P.ws + WS_ZB); bf16_t* KB = (bf16_t*)(P.ws + WS_KB);
;     const int* pos = (const int*)P.in[2]; const float* qn = P.in[12]; const float* kn = P.in[13];
;     const float qn0 = qn[lane], qn1 = qn[64 + lane], qn2 = qn[128 + lane], kn0 = kn[lane], kn1 = kn[64 + lane], kn2 = kn[128 + lane];
;     const float invf = exp2f(-(float)(lane & 31) * (13.287712379549449f / 32.f));
;     const float QSC = 0.07216878364870322f * LOG2E;
;     for (int t = GWAVE_ID; t < T_TOK; t += GWAVES) {
;         float sn, cs; sincos_red((float)pos[t] * invf, sn, cs);
;         const float kpe = bf2f(ZB[(size_t)t * ZB_LD + 1024 + lane]);
; #pragma unroll
;         for (int h = 0; h < 8; ++h) {
;             bf16_t* q = QB + (size_t)t * 1536 + h * 192;
;             float a0 = bf2f(q[lane]), a1 = bf2f(q[64 + lane]), a2 = bf2f(q[128 + lane]);
;             float rs = rsqrtf(wave_sum(a0 * a0 + a1 * a1 + a2 * a2) * (1.f / 192.f) + EPS);
.LBB0_199:
	s_and_b64 vcc, exec, s[0:1]
	s_cbranch_vccz .LBB0_204
	v_mov_b32_e32 v1, v202
	v_readlane_b32 s0, v253, 12
	v_ashrrev_i32_e32 v0, 6, v1
	s_nop 0
	v_add_u32_e32 v0, s0, v0
	s_mov_b32 s0, 0x8000
	v_cmp_gt_i32_e32 vcc, s0, v0
	s_and_saveexec_b64 s[12:13], vcc
	v_readlane_b32 s2, v252, 60
	v_readlane_b32 s6, v253, 49
	v_readlane_b32 s10, v253, 51
	v_readlane_b32 s3, v252, 61
	v_readlane_b32 s7, v253, 50
	v_readlane_b32 s11, v253, 52
	s_mov_b32 s14, 0x1fc00000
	s_movk_i32 s15, 0x7fff
	s_mov_b32 s16, 0x3baaaaab
	s_cbranch_execz .LBB0_203
	v_and_b32_e32 v4, 63, v1
	v_readlane_b32 s52, v250, 62
	v_lshlrev_b32_e32 v2, 2, v4
	v_readlane_b32 s60, v251, 6
	v_readlane_b32 s61, v251, 7
	v_readlane_b32 s62, v251, 8
	v_readlane_b32 s63, v251, 9
	s_nop 2
	global_load_dword v30, v2, s[60:61]
	global_load_dword v31, v2, s[60:61] offset:256
	global_load_dword v32, v2, s[62:63] offset:256
	global_load_dword v33, v2, s[62:63] offset:512
	global_load_dword v34, v2, s[60:61] offset:512
	global_load_dword v35, v2, s[62:63]
	v_and_b32_e32 v1, 31, v1
	v_cvt_f32_ubyte0_e32 v1, v1
	v_mul_f32_e32 v2, 0xbed49a78, v1
	s_mov_b32 s0, 0xc2fc0000
	v_cmp_gt_f32_e32 vcc, s0, v2
	v_mov_b64_e32 v[6:7], s[92:93]
	s_movk_i32 s0, 0xc00
	v_cndmask_b32_e32 v2, 0, v206, vcc
	v_fmac_f32_e32 v2, 0xbed49a78, v1
	v_exp_f32_e32 v1, v2
	v_cndmask_b32_e32 v2, 0, v207, vcc
	v_mad_i64_i32 v[6:7], s[0:1], v0, s0, v[6:7]
	v_ldexp_f32 v36, v1, v2
	v_and_b32_e32 v1, 64, v208
	v_add_u32_e32 v1, 64, v1
	v_xor_b32_e32 v2, 1, v208
	v_cmp_lt_i32_e32 vcc, v2, v1
	v_readlane_b32 s53, v250, 63
	v_readlane_b32 s54, v251, 0
	v_cndmask_b32_e32 v2, v208, v2, vcc
	v_lshlrev_b32_e32 v37, 2, v2
	v_xor_b32_e32 v2, 2, v208
	v_cmp_lt_i32_e32 vcc, v2, v1
	v_readlane_b32 s55, v251, 1
	v_readlane_b32 s56, v251, 2
	v_cndmask_b32_e32 v2, v208, v2, vcc
	v_lshlrev_b32_e32 v38, 2, v2
	v_xor_b32_e32 v2, 4, v208
	v_cmp_lt_i32_e32 vcc, v2, v1
	v_readlane_b32 s57, v251, 3
	v_readlane_b32 s58, v251, 4
	v_cndmask_b32_e32 v2, v208, v2, vcc
	v_lshlrev_b32_e32 v39, 2, v2
	v_xor_b32_e32 v2, 8, v208
	v_cmp_lt_i32_e32 vcc, v2, v1
	v_readlane_b32 s59, v251, 5
	v_readlane_b32 s64, v251, 10
	v_cndmask_b32_e32 v2, v208, v2, vcc
	v_lshlrev_b32_e32 v40, 2, v2
	v_xor_b32_e32 v2, 16, v208
	v_cmp_lt_i32_e32 vcc, v2, v1
	v_readlane_b32 s65, v251, 11
	v_readlane_b32 s66, v251, 12
	v_cndmask_b32_e32 v2, v208, v2, vcc
	v_lshlrev_b32_e32 v41, 2, v2
	v_xor_b32_e32 v2, 32, v208
	v_cmp_lt_i32_e32 vcc, v2, v1
	v_readlane_b32 s67, v251, 13
	v_readlane_b32 s0, v252, 62
	v_cndmask_b32_e32 v1, v208, v2, vcc
	v_lshlrev_b32_e32 v42, 2, v1
	v_ashrrev_i32_e32 v1, 31, v0
	v_readlane_b32 s52, v253, 26
	v_readlane_b32 s1, v252, 63
	v_cmp_gt_u32_e32 vcc, 32, v4
	v_readlane_b32 s56, v253, 30
	v_readlane_b32 s57, v253, 31
	v_lshlrev_b32_e32 v180, 1, v4
	v_lshlrev_b64 v[4:5], 12, v[0:1]
	v_mov_b64_e32 v[8:9], s[0:1]
	s_movk_i32 s0, 0x880
	v_lshl_add_u64 v[2:3], v[0:1], 2, s[56:57]
	v_lshl_add_u64 v[4:5], s[92:93], 0, v[4:5]
	v_mad_i64_i32 v[8:9], s[0:1], v0, s0, v[8:9]
	s_mov_b64 s[20:21], 0
	v_readlane_b32 s53, v253, 27
	v_readlane_b32 s54, v253, 28
	v_readlane_b32 s55, v253, 29
	v_readlane_b32 s58, v253, 32
	v_readlane_b32 s59, v253, 33
	v_readlane_b32 s60, v253, 34
	v_readlane_b32 s61, v253, 35
	v_readlane_b32 s62, v253, 36
	v_readlane_b32 s63, v253, 37
	v_readlane_b32 s64, v253, 38
	v_readlane_b32 s65, v253, 39
	v_readlane_b32 s66, v253, 40
	v_readlane_b32 s67, v253, 41
	v_min_u32_e32 v48, 23, v208
	v_lshlrev_b32_e32 v48, 7, v48
	v_add_u32_e32 v48, 0x19c00000, v48
	v_mov_b32_e32 v49, 0
	v_min_u32_e32 v54, 31, v208
	v_lshlrev_b32_e32 v54, 7, v54
	v_mov_b32_e32 v55, 0
	v_lshl_add_u64 v[54:55], v[54:55], 0, s[2:3]
	v_add_co_u32_e64 v54, s[0:1], s14, v54
	s_nop 1
	v_addc_co_u32_e64 v55, s[0:1], 0, v55, s[0:1]
.LBB0_202:
	global_load_dword v1, v[2:3], off
	s_waitcnt lgkmcnt(0)
	v_lshl_add_u64 v[18:19], v[6:7], 0, v[180:181]
	s_mov_b32 s0, 0x19c00000
	v_lshl_add_u64 v[12:13], v[8:9], 0, v[180:181]
	v_add_u32_e32 v0, s74, v0
	v_lshl_add_u64 v[2:3], v[2:3], 0, s[96:97]
	v_lshl_add_u64 v[6:7], v[6:7], 0, s[6:7]
	v_lshl_add_u64 v[8:9], v[8:9], 0, s[10:11]
	s_waitcnt vmcnt(0)
	v_lshl_add_u64 v[50:51], v[6:7], 0, v[48:49]
	global_load_dword v52, v[50:51], off
	v_lshl_add_u64 v[50:51], v[4:5], 0, v[54:55]
	global_load_dword v53, v[50:51], off
	v_cvt_f32_i32_e32 v1, v1
	v_mul_f32_e32 v1, v36, v1
	v_mul_f32_e32 v10, 0.15915494, v1
	v_rndne_f32_e32 v10, v10
	v_fmac_f32_e32 v1, 0xc0c90000, v10
	v_fmac_f32_e32 v1, 0xbafdaa22, v10
	v_add_co_u32_e64 v10, s[0:1], s0, v18
	v_mul_f32_e32 v1, 0.15915494, v1
	s_nop 0
	v_addc_co_u32_e64 v11, s[0:1], 0, v19, s[0:1]
	global_load_ushort v14, v[10:11], off offset:128
	v_sin_f32_e32 v43, v1
	v_cos_f32_e32 v1, v1
	s_waitcnt vmcnt(0)
	v_lshlrev_b32_e32 v20, 16, v14
	global_load_ushort v14, v[10:11], off
	global_load_ushort v15, v[10:11], off offset:256
	global_load_ushort v24, v[12:13], off
	s_waitcnt vmcnt(2)
	v_lshlrev_b32_e32 v14, 16, v14
	s_waitcnt vmcnt(1)
	v_lshlrev_b32_e32 v15, 16, v15
	v_pk_mul_f32 v[16:17], v[14:15], v[14:15]
	s_nop 0
	v_fma_f32 v16, v20, v20, v16
	v_add_f32_e32 v16, v16, v17
	s_nop 1
	v_mov_b32_dpp v17, v16 quad_perm:[1,0,3,2] row_mask:0xf bank_mask:0xf
	s_waitcnt lgkmcnt(0)
	v_add_f32_e32 v16, v16, v17
	s_nop 1
	v_mov_b32_dpp v17, v16 quad_perm:[2,3,0,1] row_mask:0xf bank_mask:0xf
	s_waitcnt lgkmcnt(0)
	v_add_f32_e32 v16, v16, v17
	s_nop 1
	v_mov_b32_dpp v17, v16 row_half_mirror row_mask:0xf bank_mask:0xf
	s_waitcnt lgkmcnt(0)
	v_add_f32_e32 v16, v16, v17
	s_nop 1
	v_mov_b32_dpp v17, v16 row_mirror row_mask:0xf bank_mask:0xf
	s_waitcnt lgkmcnt(0)
; __device__ __forceinline__ float bf2f(unsigned short h) { return __uint_as_float(((unsigned)h) << 16); }
; __device__ __forceinline__ unsigned short f2bf(float f) { return (unsigned short)(cvt_pk_bf16(f, 0.f) & 0xffffu); }
; __device__ __forceinline__ void pass_qk_prep(const Params& P) {
;     ...
;         for (int h = 0; h < 8; ++h) {
;             bf16_t* q = QB + (size_t)t * 1536 + h * 192;
;             float a0 = bf2f(q[lane]), a1 = bf2f(q[64 + lane]), a2 = bf2f(q[128 + lane]);
;             float rs = rsqrtf(wave_sum(a0 * a0 + a1 * a1 + a2 * a2) * (1.f / 192.f) + EPS);
;             a0 *= rs * qn0; a1 *= rs * qn1; a2 *= rs * qn2;
;             float ot = __shfl_xor(a2, 32);
;             float r2 = lane < 32 ? a2 * cs - ot * sn : a2 * cs + ot * sn;
;             q[lane] = f2bf(a0 * QSC); q[64 + lane] = f2bf(a1 * QSC); q[128 + lane] = f2bf(r2 * QSC);
;             const bf16_t* kv = KVR + (size_t)t * 2048 + h * 256;
;             float b0 = bf2f(kv[lane]), b1 = bf2f(kv[64 + lane]), b2 = kpe;
;             rs = rsqrtf(wave_sum(b0 * b0 + b1 * b1 + b2 * b2) * (1.f / 192.f) + EPS);
;             b0 *= rs * kn0; b1 *= rs * kn1; b2 *= rs * kn2;
;             ot = __shfl_xor(b2, 32);
;             r2 = lane < 32 ? b2 * cs - ot * sn : b2 * cs + ot * sn;
;             bf16_t* k = KB + (size_t)t * 1536 + h * 192;
;             k[lane] = f2bf(b0); k[64 + lane] = f2bf(b1); k[128 + lane] = f2bf(r2);
	v_add_f32_e32 v16, v16, v17
	v_mov_b32_e32 v17, v16
	s_nop 1
	v_permlane16_swap_b32 v16, v17
	s_waitcnt lgkmcnt(0)
	v_add_f32_e32 v16, v16, v17
	v_mov_b32_e32 v17, v16
	s_nop 1
	v_permlane32_swap_b32 v16, v17
	s_waitcnt lgkmcnt(0)
	v_add_f32_e32 v16, v16, v17
	v_fmamk_f32 v16, v16, 0x3baaaaab, v203
	v_cmp_gt_f32_e64 s[0:1], s71, v16
	v_mul_f32_e32 v17, 0x4b800000, v16
	s_nop 0
	v_cndmask_b32_e64 v16, v16, v17, s[0:1]
	v_rsq_f32_e32 v16, v16
	s_nop 0
	v_mul_f32_e32 v17, 0x45800000, v16
	v_cndmask_b32_e64 v16, v16, v17, s[0:1]
	v_mul_f32_e32 v17, v30, v16
	v_mul_f32_e32 v14, v17, v14
	v_mul_f32_e32 v17, v31, v16
	v_mul_f32_e32 v16, v34, v16
	v_mul_f32_e32 v15, v16, v15
	ds_bpermute_b32 v16, v42, v15
	v_mul_f32_e32 v17, v17, v20
	v_mul_f32_e32 v12, 0x3dd53b94, v17
	v_cvt_pk_bf16_f32 v12, v12, s0
	global_store_short v[10:11], v12, off offset:128
	s_waitcnt lgkmcnt(0)
	v_mul_f32_e32 v16, v43, v16
	v_cndmask_b32_e64 v16, v16, -v16, vcc
	v_fmac_f32_e32 v16, v1, v15
	v_mul_f32_e32 v12, 0x3dd53b94, v16
	v_cvt_pk_bf16_f32 v12, v12, s0
	v_mul_f32_e32 v14, 0x3dd53b94, v14
	global_store_short v[10:11], v12, off offset:256
	v_lshl_add_u64 v[12:13], v[4:5], 0, v[180:181]
	v_cvt_pk_bf16_f32 v14, v14, s0
	v_add_co_u32_e64 v12, s[0:1], s14, v12
	global_store_short v[10:11], v14, off
	s_nop 0
	v_addc_co_u32_e64 v13, s[0:1], 0, v13, s[0:1]
	global_load_ushort v14, v[12:13], off
	global_load_ushort v15, v[12:13], off offset:128
	v_lshl_add_u64 v[4:5], v[4:5], 0, s[2:3]
	s_waitcnt vmcnt(1)
	v_lshlrev_b32_e32 v20, 16, v14
	global_load_ushort v14, v[10:11], off offset:512
	s_waitcnt vmcnt(1)
	v_lshlrev_b32_e32 v21, 16, v15
	v_pk_mul_f32 v[22:23], v[20:21], v[20:21]
	s_waitcnt vmcnt(0)
	v_lshlrev_b32_e32 v25, 16, v14
	global_load_ushort v14, v[10:11], off offset:384
	global_load_ushort v15, v[10:11], off offset:640
	v_add_f32_e32 v22, v22, v23
	s_waitcnt vmcnt(1)
	v_lshlrev_b32_e32 v14, 16, v14
	s_waitcnt vmcnt(0)
	v_lshlrev_b32_e32 v15, 16, v15
	v_pk_mul_f32 v[16:17], v[14:15], v[14:15]
	s_nop 0
	v_fma_f32 v16, v25, v25, v16
	v_add_f32_e32 v16, v16, v17
	s_nop 1
	v_mov_b32_dpp v17, v16 quad_perm:[1,0,3,2] row_mask:0xf bank_mask:0xf
	s_waitcnt lgkmcnt(0)
	v_add_f32_e32 v16, v16, v17
	s_nop 1
	v_mov_b32_dpp v17, v16 quad_perm:[2,3,0,1] row_mask:0xf bank_mask:0xf
	s_waitcnt lgkmcnt(0)
	v_add_f32_e32 v16, v16, v17
	s_nop 1
	v_mov_b32_dpp v17, v16 row_half_mirror row_mask:0xf bank_mask:0xf
	s_waitcnt lgkmcnt(0)
	v_add_f32_e32 v16, v16, v17
	s_nop 1
	v_mov_b32_dpp v17, v16 row_mirror row_mask:0xf bank_mask:0xf
	s_waitcnt lgkmcnt(0)
	v_add_f32_e32 v16, v16, v17
	v_mov_b32_e32 v17, v16
	s_nop 1
	v_permlane16_swap_b32 v16, v17
	s_waitcnt lgkmcnt(0)
	v_add_f32_e32 v16, v16, v17
	v_mov_b32_e32 v17, v16
	s_nop 1
	v_permlane32_swap_b32 v16, v17
	s_waitcnt lgkmcnt(0)
	v_add_f32_e32 v16, v16, v17
	v_fmamk_f32 v16, v16, 0x3baaaaab, v203
	v_cmp_gt_f32_e64 s[0:1], s71, v16
	v_mul_f32_e32 v17, 0x4b800000, v16
	s_nop 0
	v_cndmask_b32_e64 v16, v16, v17, s[0:1]
	v_rsq_f32_e32 v16, v16
	s_nop 0
	v_mul_f32_e32 v17, 0x45800000, v16
	v_cndmask_b32_e64 v16, v16, v17, s[0:1]
	v_mul_f32_e32 v17, v30, v16
	v_mul_f32_e32 v14, v17, v14
	v_mul_f32_e32 v17, v31, v16
	v_mul_f32_e32 v16, v34, v16
	v_mul_f32_e32 v15, v16, v15
	ds_bpermute_b32 v16, v42, v15
	v_mul_f32_e32 v14, 0x3dd53b94, v14
	v_mul_f32_e32 v17, v17, v25
	v_cvt_pk_bf16_f32 v14, v14, s0
	global_store_short v[10:11], v14, off offset:384
	s_waitcnt lgkmcnt(0)
	v_mul_f32_e32 v16, v43, v16
	v_cndmask_b32_e64 v16, v16, -v16, vcc
	v_mul_f32_e32 v14, 0x3dd53b94, v17
	v_fmac_f32_e32 v16, v1, v15
	v_cvt_pk_bf16_f32 v14, v14, s0
	global_store_short v[10:11], v14, off offset:512
	v_mul_f32_e32 v14, 0x3dd53b94, v16
	v_cvt_pk_bf16_f32 v14, v14, s0
	global_store_short v[10:11], v14, off offset:640
	global_load_ushort v14, v[12:13], off offset:512
	s_waitcnt vmcnt(0)
	v_lshlrev_b32_e32 v15, 16, v14
	v_lshlrev_b32_e32 v14, 16, v24
	v_pk_mul_f32 v[16:17], v[14:15], v[14:15]
	s_nop 0
	v_add_f32_e32 v22, v16, v22
	s_nop 1
	v_mov_b32_dpp v23, v22 quad_perm:[1,0,3,2] row_mask:0xf bank_mask:0xf
	v_mov_b32_e32 v27, v17
	s_waitcnt lgkmcnt(0)
	v_add_f32_e32 v22, v22, v23
	s_nop 1
	v_mov_b32_dpp v23, v22 quad_perm:[2,3,0,1] row_mask:0xf bank_mask:0xf
	s_waitcnt lgkmcnt(0)
	v_add_f32_e32 v22, v22, v23
	s_nop 1
	v_mov_b32_dpp v23, v22 row_half_mirror row_mask:0xf bank_mask:0xf
	s_waitcnt lgkmcnt(0)
	v_add_f32_e32 v22, v22, v23
	s_nop 1
	v_mov_b32_dpp v23, v22 row_mirror row_mask:0xf bank_mask:0xf
	s_waitcnt lgkmcnt(0)
	v_add_f32_e32 v22, v22, v23
	v_mov_b32_e32 v23, v22
	s_nop 1
	v_permlane16_swap_b32 v22, v23
	s_waitcnt lgkmcnt(0)
	v_add_f32_e32 v22, v22, v23
	v_mov_b32_e32 v23, v22
	s_nop 1
	v_permlane32_swap_b32 v22, v23
	s_waitcnt lgkmcnt(0)
	v_add_f32_e32 v22, v22, v23
	v_fmamk_f32 v22, v22, 0x3baaaaab, v203
	v_cmp_gt_f32_e64 s[0:1], s71, v22
	v_mul_f32_e32 v23, 0x4b800000, v22
	s_nop 0
	v_cndmask_b32_e64 v22, v22, v23, s[0:1]
	v_rsq_f32_e32 v22, v22
	s_nop 0
	v_mul_f32_e32 v23, 0x45800000, v22
	v_cndmask_b32_e64 v22, v22, v23, s[0:1]
	v_mul_f32_e32 v23, v35, v22
	v_mul_f32_e32 v20, v23, v20
	v_mul_f32_e32 v23, v32, v22
	v_mul_f32_e32 v22, v33, v22
	v_mul_f32_e32 v22, v22, v14
	v_mul_f32_e32 v21, v23, v21
	ds_bpermute_b32 v23, v42, v22
	v_cvt_pk_bf16_f32 v20, v20, s0
	s_mov_b32 s0, 0x36000000
	v_add_co_u32_e64 v18, s[0:1], s0, v18
	s_waitcnt lgkmcnt(0)
	v_mul_f32_e32 v23, v43, v23
	v_cndmask_b32_e64 v23, v23, -v23, vcc
	v_addc_co_u32_e64 v19, s[0:1], 0, v19, s[0:1]
	v_fmac_f32_e32 v23, v1, v22
	global_load_ushort v22, v[12:13], off offset:640
	s_nop 0
	global_store_short v[18:19], v20, off
	v_cvt_pk_bf16_f32 v20, v21, s0
	global_store_short v[18:19], v20, off offset:128
	v_cvt_pk_bf16_f32 v20, v23, s0
	global_store_short v[18:19], v20, off offset:256
	global_load_ushort v20, v[10:11], off offset:896
	s_mov_b32 s0, 0x358637bd
	s_waitcnt vmcnt(4)
; __device__ __forceinline__ float bf2f(unsigned short h) { return __uint_as_float(((unsigned)h) << 16); }
; __device__ __forceinline__ unsigned short f2bf(float f) { return (unsigned short)(cvt_pk_bf16(f, 0.f) & 0xffffu); }
; __device__ __forceinline__ void pass_qk_prep(const Params& P) {
;     ...
;         for (int h = 0; h < 8; ++h) {
;             bf16_t* q = QB + (size_t)t * 1536 + h * 192;
;             float a0 = bf2f(q[lane]), a1 = bf2f(q[64 + lane]), a2 = bf2f(q[128 + lane]);
;             float rs = rsqrtf(wave_sum(a0 * a0 + a1 * a1 + a2 * a2) * (1.f / 192.f) + EPS);
;             a0 *= rs * qn0; a1 *= rs * qn1; a2 *= rs * qn2;
;             float ot = __shfl_xor(a2, 32);
;             float r2 = lane < 32 ? a2 * cs - ot * sn : a2 * cs + ot * sn;
;             q[lane] = f2bf(a0 * QSC); q[64 + lane] = f2bf(a1 * QSC); q[128 + lane] = f2bf(r2 * QSC);
;             const bf16_t* kv = KVR + (size_t)t * 2048 + h * 256;
;             float b0 = bf2f(kv[lane]), b1 = bf2f(kv[64 + lane]), b2 = kpe;
;             rs = rsqrtf(wave_sum(b0 * b0 + b1 * b1 + b2 * b2) * (1.f / 192.f) + EPS);
;             b0 *= rs * kn0; b1 *= rs * kn1; b2 *= rs * kn2;
;             ot = __shfl_xor(b2, 32);
;             r2 = lane < 32 ? b2 * cs - ot * sn : b2 * cs + ot * sn;
;             bf16_t* k = KB + (size_t)t * 1536 + h * 192;
;             k[lane] = f2bf(b0); k[64 + lane] = f2bf(b1); k[128 + lane] = f2bf(r2);
	v_lshlrev_b32_e32 v23, 16, v22
	s_waitcnt vmcnt(0)
	v_lshlrev_b32_e32 v22, 16, v20
	global_load_ushort v20, v[10:11], off offset:768
	global_load_ushort v21, v[10:11], off offset:1024
	s_waitcnt vmcnt(1)
	v_lshlrev_b32_e32 v24, 16, v20
	s_waitcnt vmcnt(0)
	v_lshlrev_b32_e32 v25, 16, v21
	v_pk_mul_f32 v[20:21], v[24:25], v[24:25]
	s_nop 0
	v_mov_b32_e32 v26, v20
	v_pk_fma_f32 v[26:27], v[22:23], v[22:23], v[26:27]
	v_pk_mov_b32 v[20:21], v[20:21], v[16:17] op_sel:[1,0]
	s_nop 0
	v_pk_add_f32 v[20:21], v[26:27], v[20:21]
	s_nop 1
	v_mov_b32_dpp v27, v21 quad_perm:[1,0,3,2] row_mask:0xf bank_mask:0xf
	v_mov_b32_dpp v26, v20 quad_perm:[1,0,3,2] row_mask:0xf bank_mask:0xf
	s_waitcnt lgkmcnt(0)
	v_pk_add_f32 v[20:21], v[20:21], v[26:27]
	s_nop 1
	v_mov_b32_dpp v27, v21 quad_perm:[2,3,0,1] row_mask:0xf bank_mask:0xf
	v_mov_b32_dpp v26, v20 quad_perm:[2,3,0,1] row_mask:0xf bank_mask:0xf
	s_waitcnt lgkmcnt(0)
	v_pk_add_f32 v[20:21], v[20:21], v[26:27]
	s_nop 1
	v_mov_b32_dpp v27, v21 row_half_mirror row_mask:0xf bank_mask:0xf
	v_mov_b32_dpp v26, v20 row_half_mirror row_mask:0xf bank_mask:0xf
	s_waitcnt lgkmcnt(0)
	v_pk_add_f32 v[20:21], v[20:21], v[26:27]
	s_nop 1
	v_mov_b32_dpp v27, v21 row_mirror row_mask:0xf bank_mask:0xf
	v_mov_b32_dpp v26, v20 row_mirror row_mask:0xf bank_mask:0xf
	s_waitcnt lgkmcnt(0)
	v_pk_add_f32 v[20:21], v[20:21], v[26:27]
	v_mov_b32_e32 v27, v21
	v_mov_b32_e32 v26, v20
	s_nop 1
	v_permlane16_swap_b32 v21, v27
	v_permlane16_swap_b32 v20, v26
	s_waitcnt lgkmcnt(0)
	v_pk_add_f32 v[20:21], v[20:21], v[26:27]
	v_mov_b32_e32 v27, v21
	v_mov_b32_e32 v26, v20
	s_nop 1
	v_permlane32_swap_b32 v21, v27
	v_permlane32_swap_b32 v20, v26
	s_waitcnt lgkmcnt(0)
	v_pk_add_f32 v[26:27], v[20:21], v[26:27]
	v_mov_b64_e32 v[20:21], s[0:1]
	v_pk_fma_f32 v[26:27], v[26:27], s[16:17], v[20:21] op_sel_hi:[1,0,0]
	s_nop 0
	v_mul_f32_e32 v28, 0x4b800000, v27
	v_cmp_gt_f32_e64 s[38:39], s71, v27
	v_cmp_gt_f32_e64 s[0:1], s71, v26
	s_nop 0
	v_cndmask_b32_e64 v27, v27, v28, s[38:39]
	v_rsq_f32_e32 v27, v27
	s_nop 0
	v_mul_f32_e32 v28, 0x45800000, v27
	v_cndmask_b32_e64 v27, v27, v28, s[38:39]
	v_mul_f32_e32 v28, v35, v27
	v_mul_f32_e32 v15, v28, v15
	v_mul_f32_e32 v28, v32, v27
	v_mul_f32_e32 v27, v33, v27
	v_mul_f32_e32 v27, v27, v14
	v_mul_f32_e32 v23, v28, v23
	ds_bpermute_b32 v28, v42, v27
	v_cvt_pk_bf16_f32 v15, v15, s0
	global_store_short v[18:19], v15, off offset:384
	v_cvt_pk_bf16_f32 v15, v23, s0
	global_store_short v[18:19], v15, off offset:512
	s_waitcnt lgkmcnt(0)
	v_mul_f32_e32 v28, v43, v28
	v_cndmask_b32_e64 v28, v28, -v28, vcc
	v_fmac_f32_e32 v28, v1, v27
	v_cvt_pk_bf16_f32 v15, v28, s0
	global_store_short v[18:19], v15, off offset:640
	v_mul_f32_e32 v15, 0x4b800000, v26
	v_cndmask_b32_e64 v15, v26, v15, s[0:1]
	v_rsq_f32_e32 v15, v15
	s_nop 0
	v_mul_f32_e32 v23, 0x45800000, v15
	v_cndmask_b32_e64 v15, v15, v23, s[0:1]
	v_mul_f32_e32 v23, v30, v15
	v_mul_f32_e32 v23, v23, v24
	v_mul_f32_e32 v24, v31, v15
	v_mul_f32_e32 v15, v34, v15
	v_mul_f32_e32 v15, v15, v25
	v_mul_f32_e32 v22, v24, v22
	ds_bpermute_b32 v24, v42, v15
	s_waitcnt lgkmcnt(0)
	v_mul_f32_e32 v24, v43, v24
	v_cndmask_b32_e64 v24, v24, -v24, vcc
	v_fmac_f32_e32 v24, v1, v15
	v_mul_f32_e32 v15, 0x3dd53b94, v23
	v_cvt_pk_bf16_f32 v15, v15, s0
	global_store_short v[10:11], v15, off offset:768
	v_mul_f32_e32 v15, 0x3dd53b94, v22
	v_cvt_pk_bf16_f32 v15, v15, s0
	global_store_short v[10:11], v15, off offset:896
	v_mul_f32_e32 v15, 0x3dd53b94, v24
	v_cvt_pk_bf16_f32 v15, v15, s0
	global_store_short v[10:11], v15, off offset:1024
	global_load_ushort v15, v[12:13], off offset:1024
	s_nop 0
	global_load_ushort v22, v[12:13], off offset:1152
	s_waitcnt vmcnt(0)
	v_lshlrev_b32_e32 v23, 16, v22
	v_lshlrev_b32_e32 v22, 16, v15
	global_load_ushort v15, v[10:11], off offset:1280
	global_load_ushort v27, v[10:11], off offset:1152
	global_load_ushort v28, v[10:11], off offset:1408
	v_pk_mul_f32 v[24:25], v[22:23], v[22:23]
	s_waitcnt vmcnt(2)
	v_lshlrev_b32_e32 v15, 16, v15
	s_waitcnt vmcnt(0)
	v_lshlrev_b32_e32 v29, 16, v28
	v_lshlrev_b32_e32 v28, 16, v27
	v_pk_mul_f32 v[44:45], v[28:29], v[28:29]
	v_mul_f32_e32 v26, v15, v15
	v_mov_b32_e32 v46, v44
	v_mov_b32_e32 v47, v24
	v_mov_b32_e32 v27, v25
	v_pk_add_f32 v[24:25], v[46:47], v[26:27]
	v_pk_mov_b32 v[26:27], v[44:45], v[16:17] op_sel:[1,0]
	s_nop 0
	v_pk_add_f32 v[24:25], v[24:25], v[26:27]
	s_nop 1
	v_mov_b32_dpp v27, v25 quad_perm:[1,0,3,2] row_mask:0xf bank_mask:0xf
	v_mov_b32_dpp v26, v24 quad_perm:[1,0,3,2] row_mask:0xf bank_mask:0xf
	s_waitcnt lgkmcnt(0)
	v_pk_add_f32 v[24:25], v[24:25], v[26:27]
	s_nop 1
	v_mov_b32_dpp v27, v25 quad_perm:[2,3,0,1] row_mask:0xf bank_mask:0xf
	v_mov_b32_dpp v26, v24 quad_perm:[2,3,0,1] row_mask:0xf bank_mask:0xf
	s_waitcnt lgkmcnt(0)
	v_pk_add_f32 v[24:25], v[24:25], v[26:27]
	s_nop 1
	v_mov_b32_dpp v27, v25 row_half_mirror row_mask:0xf bank_mask:0xf
	v_mov_b32_dpp v26, v24 row_half_mirror row_mask:0xf bank_mask:0xf
	s_waitcnt lgkmcnt(0)
	v_pk_add_f32 v[24:25], v[24:25], v[26:27]
	s_nop 1
	v_mov_b32_dpp v27, v25 row_mirror row_mask:0xf bank_mask:0xf
	v_mov_b32_dpp v26, v24 row_mirror row_mask:0xf bank_mask:0xf
	s_waitcnt lgkmcnt(0)
	v_pk_add_f32 v[24:25], v[24:25], v[26:27]
	v_mov_b32_e32 v27, v25
	v_mov_b32_e32 v26, v24
	s_nop 1
	v_permlane16_swap_b32 v25, v27
	v_permlane16_swap_b32 v24, v26
	s_waitcnt lgkmcnt(0)
	v_pk_add_f32 v[24:25], v[24:25], v[26:27]
	v_mov_b32_e32 v27, v25
	v_mov_b32_e32 v26, v24
	s_nop 1
	v_permlane32_swap_b32 v25, v27
	v_permlane32_swap_b32 v24, v26
	s_waitcnt lgkmcnt(0)
; __device__ __forceinline__ float bf2f(unsigned short h) { return __uint_as_float(((unsigned)h) << 16); }
; __device__ __forceinline__ unsigned short f2bf(float f) { return (unsigned short)(cvt_pk_bf16(f, 0.f) & 0xffffu); }
; __device__ __forceinline__ void pass_qk_prep(const Params& P) {
;     ...
;         for (int h = 0; h < 8; ++h) {
;             bf16_t* q = QB + (size_t)t * 1536 + h * 192;
;             float a0 = bf2f(q[lane]), a1 = bf2f(q[64 + lane]), a2 = bf2f(q[128 + lane]);
;             float rs = rsqrtf(wave_sum(a0 * a0 + a1 * a1 + a2 * a2) * (1.f / 192.f) + EPS);
;             a0 *= rs * qn0; a1 *= rs * qn1; a2 *= rs * qn2;
;             float ot = __shfl_xor(a2, 32);
;             float r2 = lane < 32 ? a2 * cs - ot * sn : a2 * cs + ot * sn;
;             q[lane] = f2bf(a0 * QSC); q[64 + lane] = f2bf(a1 * QSC); q[128 + lane] = f2bf(r2 * QSC);
;             const bf16_t* kv = KVR + (size_t)t * 2048 + h * 256;
;             float b0 = bf2f(kv[lane]), b1 = bf2f(kv[64 + lane]), b2 = kpe;
;             rs = rsqrtf(wave_sum(b0 * b0 + b1 * b1 + b2 * b2) * (1.f / 192.f) + EPS);
;             b0 *= rs * kn0; b1 *= rs * kn1; b2 *= rs * kn2;
;             ot = __shfl_xor(b2, 32);
;             r2 = lane < 32 ? b2 * cs - ot * sn : b2 * cs + ot * sn;
;             bf16_t* k = KB + (size_t)t * 1536 + h * 192;
;             k[lane] = f2bf(b0); k[64 + lane] = f2bf(b1); k[128 + lane] = f2bf(r2);
	v_pk_add_f32 v[24:25], v[24:25], v[26:27]
	s_nop 0
	v_pk_fma_f32 v[24:25], v[24:25], s[16:17], v[20:21] op_sel_hi:[1,0,0]
	s_nop 0
	v_mul_f32_e32 v26, 0x4b800000, v25
	v_cmp_gt_f32_e64 s[38:39], s71, v25
	v_cmp_gt_f32_e64 s[0:1], s71, v24
	s_nop 0
	v_cndmask_b32_e64 v25, v25, v26, s[38:39]
	v_rsq_f32_e32 v25, v25
	s_nop 0
	v_mul_f32_e32 v26, 0x45800000, v25
	v_cndmask_b32_e64 v25, v25, v26, s[38:39]
	v_mul_f32_e32 v26, v35, v25
	v_mul_f32_e32 v22, v26, v22
	v_mul_f32_e32 v26, v32, v25
	v_mul_f32_e32 v25, v33, v25
	v_mul_f32_e32 v25, v25, v14
	v_mul_f32_e32 v23, v26, v23
	ds_bpermute_b32 v26, v42, v25
	v_cvt_pk_bf16_f32 v22, v22, s0
	global_store_short v[18:19], v22, off offset:768
	v_cvt_pk_bf16_f32 v22, v23, s0
	global_store_short v[18:19], v22, off offset:896
	s_waitcnt lgkmcnt(0)
	v_mul_f32_e32 v26, v43, v26
	v_cndmask_b32_e64 v26, v26, -v26, vcc
	v_fmac_f32_e32 v26, v1, v25
	v_cvt_pk_bf16_f32 v22, v26, s0
	global_store_short v[18:19], v22, off offset:1024
	v_mul_f32_e32 v22, 0x4b800000, v24
	v_cndmask_b32_e64 v22, v24, v22, s[0:1]
	v_rsq_f32_e32 v22, v22
	s_nop 0
	v_mul_f32_e32 v23, 0x45800000, v22
	v_cndmask_b32_e64 v22, v22, v23, s[0:1]
	v_mul_f32_e32 v23, v30, v22
	v_mul_f32_e32 v24, v31, v22
	v_mul_f32_e32 v22, v34, v22
	v_mul_f32_e32 v22, v22, v29
	v_mul_f32_e32 v15, v24, v15
	ds_bpermute_b32 v24, v42, v22
	v_mul_f32_e32 v15, 0x3dd53b94, v15
	v_mul_f32_e32 v23, v23, v28
	v_cvt_pk_bf16_f32 v15, v15, s0
	global_store_short v[10:11], v15, off offset:1280
	s_waitcnt lgkmcnt(0)
	v_mul_f32_e32 v24, v43, v24
	v_cndmask_b32_e64 v24, v24, -v24, vcc
	v_fmac_f32_e32 v24, v1, v22
	v_mul_f32_e32 v22, 0x3dd53b94, v23
	v_mul_f32_e32 v15, 0x3dd53b94, v24
	v_cvt_pk_bf16_f32 v22, v22, s0
	v_cvt_pk_bf16_f32 v15, v15, s0
	global_store_short v[10:11], v22, off offset:1152
	global_store_short v[10:11], v15, off offset:1408
	global_load_ushort v15, v[12:13], off offset:1536
	s_nop 0
	global_load_ushort v22, v[12:13], off offset:1664
	s_waitcnt vmcnt(0)
	v_lshlrev_b32_e32 v23, 16, v22
	v_lshlrev_b32_e32 v22, 16, v15
	global_load_ushort v15, v[10:11], off offset:1664
	global_load_ushort v27, v[10:11], off offset:1536
	global_load_ushort v28, v[10:11], off offset:1792
	v_pk_mul_f32 v[24:25], v[22:23], v[22:23]
	s_waitcnt vmcnt(2)
	v_lshlrev_b32_e32 v15, 16, v15
	s_waitcnt vmcnt(0)
	v_lshlrev_b32_e32 v29, 16, v28
	v_lshlrev_b32_e32 v28, 16, v27
	v_pk_mul_f32 v[44:45], v[28:29], v[28:29]
	v_mul_f32_e32 v26, v15, v15
	v_mov_b32_e32 v46, v44
	v_mov_b32_e32 v47, v24
	v_mov_b32_e32 v27, v25
	v_pk_add_f32 v[24:25], v[46:47], v[26:27]
	v_pk_mov_b32 v[26:27], v[44:45], v[16:17] op_sel:[1,0]
	s_nop 0
	v_pk_add_f32 v[24:25], v[24:25], v[26:27]
	s_nop 1
	v_mov_b32_dpp v27, v25 quad_perm:[1,0,3,2] row_mask:0xf bank_mask:0xf
	v_mov_b32_dpp v26, v24 quad_perm:[1,0,3,2] row_mask:0xf bank_mask:0xf
	s_waitcnt lgkmcnt(0)
	v_pk_add_f32 v[24:25], v[24:25], v[26:27]
	s_nop 1
	v_mov_b32_dpp v27, v25 quad_perm:[2,3,0,1] row_mask:0xf bank_mask:0xf
	v_mov_b32_dpp v26, v24 quad_perm:[2,3,0,1] row_mask:0xf bank_mask:0xf
	s_waitcnt lgkmcnt(0)
	v_pk_add_f32 v[24:25], v[24:25], v[26:27]
	s_nop 1
	v_mov_b32_dpp v27, v25 row_half_mirror row_mask:0xf bank_mask:0xf
	v_mov_b32_dpp v26, v24 row_half_mirror row_mask:0xf bank_mask:0xf
	s_waitcnt lgkmcnt(0)
	v_pk_add_f32 v[24:25], v[24:25], v[26:27]
	s_nop 1
	v_mov_b32_dpp v27, v25 row_mirror row_mask:0xf bank_mask:0xf
	v_mov_b32_dpp v26, v24 row_mirror row_mask:0xf bank_mask:0xf
	s_waitcnt lgkmcnt(0)
	v_pk_add_f32 v[24:25], v[24:25], v[26:27]
	v_mov_b32_e32 v27, v25
	v_mov_b32_e32 v26, v24
	s_nop 1
	v_permlane16_swap_b32 v25, v27
	v_permlane16_swap_b32 v24, v26
	s_waitcnt lgkmcnt(0)
	v_pk_add_f32 v[24:25], v[24:25], v[26:27]
	v_mov_b32_e32 v27, v25
	v_mov_b32_e32 v26, v24
	s_nop 1
	v_permlane32_swap_b32 v25, v27
	v_permlane32_swap_b32 v24, v26
	s_waitcnt lgkmcnt(0)
	v_pk_add_f32 v[24:25], v[24:25], v[26:27]
	s_nop 0
	v_pk_fma_f32 v[24:25], v[24:25], s[16:17], v[20:21] op_sel_hi:[1,0,0]
	s_nop 0
	v_mul_f32_e32 v26, 0x4b800000, v25
	v_cmp_gt_f32_e64 s[38:39], s71, v25
	v_cmp_gt_f32_e64 s[0:1], s71, v24
	s_nop 0
	v_cndmask_b32_e64 v25, v25, v26, s[38:39]
	v_rsq_f32_e32 v25, v25
	s_nop 0
	v_mul_f32_e32 v26, 0x45800000, v25
	v_cndmask_b32_e64 v25, v25, v26, s[38:39]
	v_mul_f32_e32 v26, v35, v25
	v_mul_f32_e32 v22, v26, v22
	v_mul_f32_e32 v26, v32, v25
	v_mul_f32_e32 v25, v33, v25
	v_mul_f32_e32 v25, v25, v14
	v_mul_f32_e32 v23, v26, v23
	ds_bpermute_b32 v26, v42, v25
	v_cvt_pk_bf16_f32 v22, v22, s0
	global_store_short v[18:19], v22, off offset:1152
	v_cvt_pk_bf16_f32 v22, v23, s0
	global_store_short v[18:19], v22, off offset:1280
	s_waitcnt lgkmcnt(0)
	v_mul_f32_e32 v26, v43, v26
	v_cndmask_b32_e64 v26, v26, -v26, vcc
	v_fmac_f32_e32 v26, v1, v25
	v_cvt_pk_bf16_f32 v22, v26, s0
	global_store_short v[18:19], v22, off offset:1408
	v_mul_f32_e32 v22, 0x4b800000, v24
	v_cndmask_b32_e64 v22, v24, v22, s[0:1]
	v_rsq_f32_e32 v22, v22
	s_nop 0
	v_mul_f32_e32 v23, 0x45800000, v22
	v_cndmask_b32_e64 v22, v22, v23, s[0:1]
	v_mul_f32_e32 v23, v30, v22
	v_mul_f32_e32 v24, v31, v22
	v_mul_f32_e32 v22, v34, v22
	v_mul_f32_e32 v22, v22, v29
	v_mul_f32_e32 v15, v24, v15
	ds_bpermute_b32 v24, v42, v22
	v_mul_f32_e32 v15, 0x3dd53b94, v15
	v_mul_f32_e32 v23, v23, v28
	v_cvt_pk_bf16_f32 v15, v15, s0
	global_store_short v[10:11], v15, off offset:1664
	s_waitcnt lgkmcnt(0)
	v_mul_f32_e32 v24, v43, v24
	v_cndmask_b32_e64 v24, v24, -v24, vcc
	v_fmac_f32_e32 v24, v1, v22
	v_mul_f32_e32 v22, 0x3dd53b94, v23
	v_mul_f32_e32 v15, 0x3dd53b94, v24
	v_cvt_pk_bf16_f32 v22, v22, s0
	v_cvt_pk_bf16_f32 v15, v15, s0
	global_store_short v[10:11], v22, off offset:1536
	global_store_short v[10:11], v15, off offset:1792
	global_load_ushort v15, v[12:13], off offset:2048
	s_nop 0
	global_load_ushort v22, v[12:13], off offset:2176
	s_waitcnt vmcnt(0)
; __device__ __forceinline__ float bf2f(unsigned short h) { return __uint_as_float(((unsigned)h) << 16); }
; __device__ __forceinline__ unsigned short f2bf(float f) { return (unsigned short)(cvt_pk_bf16(f, 0.f) & 0xffffu); }
; __device__ __forceinline__ void pass_qk_prep(const Params& P) {
;     ...
;         for (int h = 0; h < 8; ++h) {
;             bf16_t* q = QB + (size_t)t * 1536 + h * 192;
;             float a0 = bf2f(q[lane]), a1 = bf2f(q[64 + lane]), a2 = bf2f(q[128 + lane]);
;             float rs = rsqrtf(wave_sum(a0 * a0 + a1 * a1 + a2 * a2) * (1.f / 192.f) + EPS);
;             a0 *= rs * qn0; a1 *= rs * qn1; a2 *= rs * qn2;
;             float ot = __shfl_xor(a2, 32);
;             float r2 = lane < 32 ? a2 * cs - ot * sn : a2 * cs + ot * sn;
;             q[lane] = f2bf(a0 * QSC); q[64 + lane] = f2bf(a1 * QSC); q[128 + lane] = f2bf(r2 * QSC);
;             const bf16_t* kv = KVR + (size_t)t * 2048 + h * 256;
;             float b0 = bf2f(kv[lane]), b1 = bf2f(kv[64 + lane]), b2 = kpe;
;             rs = rsqrtf(wave_sum(b0 * b0 + b1 * b1 + b2 * b2) * (1.f / 192.f) + EPS);
;             b0 *= rs * kn0; b1 *= rs * kn1; b2 *= rs * kn2;
;             ot = __shfl_xor(b2, 32);
;             r2 = lane < 32 ? b2 * cs - ot * sn : b2 * cs + ot * sn;
;             bf16_t* k = KB + (size_t)t * 1536 + h * 192;
;             k[lane] = f2bf(b0); k[64 + lane] = f2bf(b1); k[128 + lane] = f2bf(r2);
	v_lshlrev_b32_e32 v23, 16, v22
	v_lshlrev_b32_e32 v22, 16, v15
	global_load_ushort v15, v[10:11], off offset:2048
	global_load_ushort v27, v[10:11], off offset:1920
	global_load_ushort v28, v[10:11], off offset:2176
	v_pk_mul_f32 v[24:25], v[22:23], v[22:23]
	s_waitcnt vmcnt(2)
	v_lshlrev_b32_e32 v15, 16, v15
	s_waitcnt vmcnt(0)
	v_lshlrev_b32_e32 v29, 16, v28
	v_lshlrev_b32_e32 v28, 16, v27
	v_pk_mul_f32 v[44:45], v[28:29], v[28:29]
	v_mul_f32_e32 v26, v15, v15
	v_mov_b32_e32 v46, v44
	v_mov_b32_e32 v47, v24
	v_mov_b32_e32 v27, v25
	v_pk_add_f32 v[24:25], v[46:47], v[26:27]
	v_pk_mov_b32 v[26:27], v[44:45], v[16:17] op_sel:[1,0]
	s_nop 0
	v_pk_add_f32 v[24:25], v[24:25], v[26:27]
	s_nop 1
	v_mov_b32_dpp v27, v25 quad_perm:[1,0,3,2] row_mask:0xf bank_mask:0xf
	v_mov_b32_dpp v26, v24 quad_perm:[1,0,3,2] row_mask:0xf bank_mask:0xf
	s_waitcnt lgkmcnt(0)
	v_pk_add_f32 v[24:25], v[24:25], v[26:27]
	s_nop 1
	v_mov_b32_dpp v27, v25 quad_perm:[2,3,0,1] row_mask:0xf bank_mask:0xf
	v_mov_b32_dpp v26, v24 quad_perm:[2,3,0,1] row_mask:0xf bank_mask:0xf
	s_waitcnt lgkmcnt(0)
	v_pk_add_f32 v[24:25], v[24:25], v[26:27]
	s_nop 1
	v_mov_b32_dpp v27, v25 row_half_mirror row_mask:0xf bank_mask:0xf
	v_mov_b32_dpp v26, v24 row_half_mirror row_mask:0xf bank_mask:0xf
	s_waitcnt lgkmcnt(0)
	v_pk_add_f32 v[24:25], v[24:25], v[26:27]
	s_nop 1
	v_mov_b32_dpp v27, v25 row_mirror row_mask:0xf bank_mask:0xf
	v_mov_b32_dpp v26, v24 row_mirror row_mask:0xf bank_mask:0xf
	s_waitcnt lgkmcnt(0)
	v_pk_add_f32 v[24:25], v[24:25], v[26:27]
	v_mov_b32_e32 v27, v25
	v_mov_b32_e32 v26, v24
	s_nop 1
	v_permlane16_swap_b32 v25, v27
	v_permlane16_swap_b32 v24, v26
	s_waitcnt lgkmcnt(0)
	v_pk_add_f32 v[24:25], v[24:25], v[26:27]
	v_mov_b32_e32 v27, v25
	v_mov_b32_e32 v26, v24
	s_nop 1
	v_permlane32_swap_b32 v25, v27
	v_permlane32_swap_b32 v24, v26
	s_waitcnt lgkmcnt(0)
	v_pk_add_f32 v[24:25], v[24:25], v[26:27]
	s_nop 0
	v_pk_fma_f32 v[24:25], v[24:25], s[16:17], v[20:21] op_sel_hi:[1,0,0]
	s_nop 0
	v_mul_f32_e32 v26, 0x4b800000, v25
	v_cmp_gt_f32_e64 s[38:39], s71, v25
	v_cmp_gt_f32_e64 s[0:1], s71, v24
	s_nop 0
	v_cndmask_b32_e64 v25, v25, v26, s[38:39]
	v_rsq_f32_e32 v25, v25
	s_nop 0
	v_mul_f32_e32 v26, 0x45800000, v25
	v_cndmask_b32_e64 v25, v25, v26, s[38:39]
	v_mul_f32_e32 v26, v35, v25
	v_mul_f32_e32 v22, v26, v22
	v_mul_f32_e32 v26, v32, v25
	v_mul_f32_e32 v25, v33, v25
	v_mul_f32_e32 v25, v25, v14
	v_mul_f32_e32 v23, v26, v23
	ds_bpermute_b32 v26, v42, v25
	v_cvt_pk_bf16_f32 v22, v22, s0
	global_store_short v[18:19], v22, off offset:1536
	v_cvt_pk_bf16_f32 v22, v23, s0
	global_store_short v[18:19], v22, off offset:1664
	s_waitcnt lgkmcnt(0)
	v_mul_f32_e32 v26, v43, v26
	v_cndmask_b32_e64 v26, v26, -v26, vcc
	v_fmac_f32_e32 v26, v1, v25
	v_cvt_pk_bf16_f32 v22, v26, s0
	global_store_short v[18:19], v22, off offset:1792
	v_mul_f32_e32 v22, 0x4b800000, v24
	v_cndmask_b32_e64 v22, v24, v22, s[0:1]
	v_rsq_f32_e32 v22, v22
	s_nop 0
	v_mul_f32_e32 v23, 0x45800000, v22
	v_cndmask_b32_e64 v22, v22, v23, s[0:1]
	v_mul_f32_e32 v23, v30, v22
	v_mul_f32_e32 v24, v31, v22
	v_mul_f32_e32 v22, v34, v22
	v_mul_f32_e32 v22, v22, v29
	v_mul_f32_e32 v15, v24, v15
	ds_bpermute_b32 v24, v42, v22
	v_mul_f32_e32 v15, 0x3dd53b94, v15
	v_mul_f32_e32 v23, v23, v28
	v_cvt_pk_bf16_f32 v15, v15, s0
	global_store_short v[10:11], v15, off offset:2048
	s_waitcnt lgkmcnt(0)
	v_mul_f32_e32 v24, v43, v24
	v_cndmask_b32_e64 v24, v24, -v24, vcc
	v_fmac_f32_e32 v24, v1, v22
	v_mul_f32_e32 v22, 0x3dd53b94, v23
	v_mul_f32_e32 v15, 0x3dd53b94, v24
	v_cvt_pk_bf16_f32 v22, v22, s0
	v_cvt_pk_bf16_f32 v15, v15, s0
	global_store_short v[10:11], v22, off offset:1920
	global_store_short v[10:11], v15, off offset:2176
	global_load_ushort v15, v[12:13], off offset:2560
	s_nop 0
	global_load_ushort v22, v[12:13], off offset:2688
	s_waitcnt vmcnt(0)
	v_lshlrev_b32_e32 v23, 16, v22
	v_lshlrev_b32_e32 v22, 16, v15
	global_load_ushort v15, v[10:11], off offset:2432
	global_load_ushort v27, v[10:11], off offset:2304
	global_load_ushort v28, v[10:11], off offset:2560
	v_pk_mul_f32 v[24:25], v[22:23], v[22:23]
	s_waitcnt vmcnt(2)
	v_lshlrev_b32_e32 v15, 16, v15
	s_waitcnt vmcnt(0)
	v_lshlrev_b32_e32 v29, 16, v28
	v_lshlrev_b32_e32 v28, 16, v27
	v_pk_mul_f32 v[44:45], v[28:29], v[28:29]
	v_mul_f32_e32 v26, v15, v15
	v_mov_b32_e32 v46, v44
	v_mov_b32_e32 v47, v24
	v_mov_b32_e32 v27, v25
	v_pk_add_f32 v[24:25], v[46:47], v[26:27]
	v_pk_mov_b32 v[26:27], v[44:45], v[16:17] op_sel:[1,0]
	s_nop 0
	v_pk_add_f32 v[24:25], v[24:25], v[26:27]
	s_nop 1
	v_mov_b32_dpp v27, v25 quad_perm:[1,0,3,2] row_mask:0xf bank_mask:0xf
	v_mov_b32_dpp v26, v24 quad_perm:[1,0,3,2] row_mask:0xf bank_mask:0xf
	s_waitcnt lgkmcnt(0)
	v_pk_add_f32 v[24:25], v[24:25], v[26:27]
	s_nop 1
	v_mov_b32_dpp v27, v25 quad_perm:[2,3,0,1] row_mask:0xf bank_mask:0xf
	v_mov_b32_dpp v26, v24 quad_perm:[2,3,0,1] row_mask:0xf bank_mask:0xf
	s_waitcnt lgkmcnt(0)
	v_pk_add_f32 v[24:25], v[24:25], v[26:27]
	s_nop 1
	v_mov_b32_dpp v27, v25 row_half_mirror row_mask:0xf bank_mask:0xf
	v_mov_b32_dpp v26, v24 row_half_mirror row_mask:0xf bank_mask:0xf
	s_waitcnt lgkmcnt(0)
	v_pk_add_f32 v[24:25], v[24:25], v[26:27]
	s_nop 1
	v_mov_b32_dpp v27, v25 row_mirror row_mask:0xf bank_mask:0xf
	v_mov_b32_dpp v26, v24 row_mirror row_mask:0xf bank_mask:0xf
	s_waitcnt lgkmcnt(0)
	v_pk_add_f32 v[24:25], v[24:25], v[26:27]
	v_mov_b32_e32 v27, v25
	v_mov_b32_e32 v26, v24
	s_nop 1
	v_permlane16_swap_b32 v25, v27
	v_permlane16_swap_b32 v24, v26
	s_waitcnt lgkmcnt(0)
	v_pk_add_f32 v[24:25], v[24:25], v[26:27]
	v_mov_b32_e32 v27, v25
	v_mov_b32_e32 v26, v24
	s_nop 1
	v_permlane32_swap_b32 v25, v27
	v_permlane32_swap_b32 v24, v26
	s_waitcnt lgkmcnt(0)
; __device__ __forceinline__ float bf2f(unsigned short h) { return __uint_as_float(((unsigned)h) << 16); }
; __device__ __forceinline__ unsigned short f2bf(float f) { return (unsigned short)(cvt_pk_bf16(f, 0.f) & 0xffffu); }
; __device__ __forceinline__ void pass_qk_prep(const Params& P) {
;     ...
;         for (int h = 0; h < 8; ++h) {
;             bf16_t* q = QB + (size_t)t * 1536 + h * 192;
;             float a0 = bf2f(q[lane]), a1 = bf2f(q[64 + lane]), a2 = bf2f(q[128 + lane]);
;             float rs = rsqrtf(wave_sum(a0 * a0 + a1 * a1 + a2 * a2) * (1.f / 192.f) + EPS);
;             a0 *= rs * qn0; a1 *= rs * qn1; a2 *= rs * qn2;
;             float ot = __shfl_xor(a2, 32);
;             float r2 = lane < 32 ? a2 * cs - ot * sn : a2 * cs + ot * sn;
;             q[lane] = f2bf(a0 * QSC); q[64 + lane] = f2bf(a1 * QSC); q[128 + lane] = f2bf(r2 * QSC);
;             const bf16_t* kv = KVR + (size_t)t * 2048 + h * 256;
;             float b0 = bf2f(kv[lane]), b1 = bf2f(kv[64 + lane]), b2 = kpe;
;             rs = rsqrtf(wave_sum(b0 * b0 + b1 * b1 + b2 * b2) * (1.f / 192.f) + EPS);
;             b0 *= rs * kn0; b1 *= rs * kn1; b2 *= rs * kn2;
;             ot = __shfl_xor(b2, 32);
;             r2 = lane < 32 ? b2 * cs - ot * sn : b2 * cs + ot * sn;
;             bf16_t* k = KB + (size_t)t * 1536 + h * 192;
;             k[lane] = f2bf(b0); k[64 + lane] = f2bf(b1); k[128 + lane] = f2bf(r2);
	v_pk_add_f32 v[24:25], v[24:25], v[26:27]
	s_nop 0
	v_pk_fma_f32 v[24:25], v[24:25], s[16:17], v[20:21] op_sel_hi:[1,0,0]
	s_nop 0
	v_mul_f32_e32 v26, 0x4b800000, v25
	v_cmp_gt_f32_e64 s[38:39], s71, v25
	v_cmp_gt_f32_e64 s[0:1], s71, v24
	s_nop 0
	v_cndmask_b32_e64 v25, v25, v26, s[38:39]
	v_rsq_f32_e32 v25, v25
	s_nop 0
	v_mul_f32_e32 v26, 0x45800000, v25
	v_cndmask_b32_e64 v25, v25, v26, s[38:39]
	v_mul_f32_e32 v26, v35, v25
	v_mul_f32_e32 v22, v26, v22
	v_mul_f32_e32 v26, v32, v25
	v_mul_f32_e32 v25, v33, v25
	v_mul_f32_e32 v25, v25, v14
	v_mul_f32_e32 v23, v26, v23
	ds_bpermute_b32 v26, v42, v25
	v_cvt_pk_bf16_f32 v22, v22, s0
	global_store_short v[18:19], v22, off offset:1920
	v_cvt_pk_bf16_f32 v22, v23, s0
	global_store_short v[18:19], v22, off offset:2048
	s_waitcnt lgkmcnt(0)
	v_mul_f32_e32 v26, v43, v26
	v_cndmask_b32_e64 v26, v26, -v26, vcc
	v_fmac_f32_e32 v26, v1, v25
	v_cvt_pk_bf16_f32 v22, v26, s0
	global_store_short v[18:19], v22, off offset:2176
	v_mul_f32_e32 v22, 0x4b800000, v24
	v_cndmask_b32_e64 v22, v24, v22, s[0:1]
	v_rsq_f32_e32 v22, v22
	s_nop 0
	v_mul_f32_e32 v23, 0x45800000, v22
	v_cndmask_b32_e64 v22, v22, v23, s[0:1]
	v_mul_f32_e32 v23, v30, v22
	v_mul_f32_e32 v24, v31, v22
	v_mul_f32_e32 v22, v34, v22
	v_mul_f32_e32 v22, v22, v29
	v_mul_f32_e32 v15, v24, v15
	ds_bpermute_b32 v24, v42, v22
	v_mul_f32_e32 v15, 0x3dd53b94, v15
	v_mul_f32_e32 v23, v23, v28
	v_cvt_pk_bf16_f32 v15, v15, s0
	global_store_short v[10:11], v15, off offset:2432
	s_waitcnt lgkmcnt(0)
	v_mul_f32_e32 v24, v43, v24
	v_cndmask_b32_e64 v24, v24, -v24, vcc
	v_fmac_f32_e32 v24, v1, v22
	v_mul_f32_e32 v22, 0x3dd53b94, v23
	v_mul_f32_e32 v15, 0x3dd53b94, v24
	v_cvt_pk_bf16_f32 v22, v22, s0
	v_cvt_pk_bf16_f32 v15, v15, s0
	global_store_short v[10:11], v22, off offset:2304
	global_store_short v[10:11], v15, off offset:2560
	global_load_ushort v15, v[12:13], off offset:3072
	s_nop 0
	global_load_ushort v22, v[12:13], off offset:3200
	s_waitcnt vmcnt(0)
	v_lshlrev_b32_e32 v23, 16, v22
	v_lshlrev_b32_e32 v22, 16, v15
	global_load_ushort v15, v[10:11], off offset:2816
	global_load_ushort v27, v[10:11], off offset:2688
	global_load_ushort v28, v[10:11], off offset:2944
	v_pk_mul_f32 v[24:25], v[22:23], v[22:23]
	s_waitcnt vmcnt(2)
	v_lshlrev_b32_e32 v15, 16, v15
	s_waitcnt vmcnt(0)
	v_lshlrev_b32_e32 v29, 16, v28
	v_lshlrev_b32_e32 v28, 16, v27
	v_pk_mul_f32 v[44:45], v[28:29], v[28:29]
	v_mul_f32_e32 v26, v15, v15
	v_mov_b32_e32 v46, v44
	v_mov_b32_e32 v47, v24
	v_mov_b32_e32 v27, v25
	v_pk_add_f32 v[24:25], v[46:47], v[26:27]
	v_pk_mov_b32 v[26:27], v[44:45], v[16:17] op_sel:[1,0]
	s_nop 0
	v_pk_add_f32 v[24:25], v[24:25], v[26:27]
	s_nop 1
	v_mov_b32_dpp v27, v25 quad_perm:[1,0,3,2] row_mask:0xf bank_mask:0xf
	v_mov_b32_dpp v26, v24 quad_perm:[1,0,3,2] row_mask:0xf bank_mask:0xf
	s_waitcnt lgkmcnt(0)
	v_pk_add_f32 v[24:25], v[24:25], v[26:27]
	s_nop 1
	v_mov_b32_dpp v27, v25 quad_perm:[2,3,0,1] row_mask:0xf bank_mask:0xf
	v_mov_b32_dpp v26, v24 quad_perm:[2,3,0,1] row_mask:0xf bank_mask:0xf
	s_waitcnt lgkmcnt(0)
	v_pk_add_f32 v[24:25], v[24:25], v[26:27]
	s_nop 1
	v_mov_b32_dpp v27, v25 row_half_mirror row_mask:0xf bank_mask:0xf
	v_mov_b32_dpp v26, v24 row_half_mirror row_mask:0xf bank_mask:0xf
	s_waitcnt lgkmcnt(0)
	v_pk_add_f32 v[24:25], v[24:25], v[26:27]
	s_nop 1
	v_mov_b32_dpp v27, v25 row_mirror row_mask:0xf bank_mask:0xf
	v_mov_b32_dpp v26, v24 row_mirror row_mask:0xf bank_mask:0xf
	s_waitcnt lgkmcnt(0)
	v_pk_add_f32 v[24:25], v[24:25], v[26:27]
	v_mov_b32_e32 v27, v25
	v_mov_b32_e32 v26, v24
	s_nop 1
	v_permlane16_swap_b32 v25, v27
	v_permlane16_swap_b32 v24, v26
	s_waitcnt lgkmcnt(0)
	v_pk_add_f32 v[24:25], v[24:25], v[26:27]
	v_mov_b32_e32 v27, v25
	v_mov_b32_e32 v26, v24
	s_nop 1
	v_permlane32_swap_b32 v25, v27
	v_permlane32_swap_b32 v24, v26
	s_waitcnt lgkmcnt(0)
; __device__ __forceinline__ float bf2f(unsigned short h) { return __uint_as_float(((unsigned)h) << 16); }
; __device__ __forceinline__ unsigned short f2bf(float f) { return (unsigned short)(cvt_pk_bf16(f, 0.f) & 0xffffu); }
; __device__ __forceinline__ void pass_qk_prep(const Params& P) {
;     ...
;         for (int h = 0; h < 8; ++h) {
;             bf16_t* q = QB + (size_t)t * 1536 + h * 192;
;             float a0 = bf2f(q[lane]), a1 = bf2f(q[64 + lane]), a2 = bf2f(q[128 + lane]);
;             float rs = rsqrtf(wave_sum(a0 * a0 + a1 * a1 + a2 * a2) * (1.f / 192.f) + EPS);
;             a0 *= rs * qn0; a1 *= rs * qn1; a2 *= rs * qn2;
;             float ot = __shfl_xor(a2, 32);
;             float r2 = lane < 32 ? a2 * cs - ot * sn : a2 * cs + ot * sn;
;             q[lane] = f2bf(a0 * QSC); q[64 + lane] = f2bf(a1 * QSC); q[128 + lane] = f2bf(r2 * QSC);
;             const bf16_t* kv = KVR + (size_t)t * 2048 + h * 256;
;             float b0 = bf2f(kv[lane]), b1 = bf2f(kv[64 + lane]), b2 = kpe;
;             rs = rsqrtf(wave_sum(b0 * b0 + b1 * b1 + b2 * b2) * (1.f / 192.f) + EPS);
;             b0 *= rs * kn0; b1 *= rs * kn1; b2 *= rs * kn2;
;             ot = __shfl_xor(b2, 32);
;             r2 = lane < 32 ? b2 * cs - ot * sn : b2 * cs + ot * sn;
;             bf16_t* k = KB + (size_t)t * 1536 + h * 192;
;             k[lane] = f2bf(b0); k[64 + lane] = f2bf(b1); k[128 + lane] = f2bf(r2);
;         }
;     }
	v_pk_add_f32 v[24:25], v[24:25], v[26:27]
	s_nop 0
	v_pk_fma_f32 v[20:21], v[24:25], s[16:17], v[20:21] op_sel_hi:[1,0,0]
	s_nop 0
	v_mul_f32_e32 v17, 0x4b800000, v21
	v_cmp_gt_f32_e64 s[38:39], s71, v21
	v_cmp_gt_f32_e64 s[0:1], s71, v20
	s_nop 0
	v_cndmask_b32_e64 v17, v21, v17, s[38:39]
	v_rsq_f32_e32 v17, v17
	s_nop 0
	v_mul_f32_e32 v21, 0x45800000, v17
	v_cndmask_b32_e64 v17, v17, v21, s[38:39]
	v_mul_f32_e32 v21, v35, v17
	v_mul_f32_e32 v21, v21, v22
	v_mul_f32_e32 v22, v32, v17
	v_mul_f32_e32 v17, v33, v17
	v_mul_f32_e32 v17, v17, v14
	v_mul_f32_e32 v22, v22, v23
	ds_bpermute_b32 v23, v42, v17
	s_waitcnt lgkmcnt(0)
	v_mul_f32_e32 v23, v43, v23
	v_cndmask_b32_e64 v23, v23, -v23, vcc
	v_fmac_f32_e32 v23, v1, v17
	v_cvt_pk_bf16_f32 v17, v21, s0
	global_store_short v[18:19], v17, off offset:2304
	v_cvt_pk_bf16_f32 v17, v22, s0
	global_store_short v[18:19], v17, off offset:2432
	v_cvt_pk_bf16_f32 v17, v23, s0
	global_store_short v[18:19], v17, off offset:2560
	v_mul_f32_e32 v17, 0x4b800000, v20
	v_cndmask_b32_e64 v17, v20, v17, s[0:1]
	v_rsq_f32_e32 v17, v17
	s_nop 0
	v_mul_f32_e32 v20, 0x45800000, v17
	v_cndmask_b32_e64 v17, v17, v20, s[0:1]
	v_mul_f32_e32 v20, v30, v17
	v_mul_f32_e32 v21, v31, v17
	v_mul_f32_e32 v17, v34, v17
	v_mul_f32_e32 v17, v17, v29
	v_mul_f32_e32 v15, v21, v15
	ds_bpermute_b32 v21, v42, v17
	v_mul_f32_e32 v15, 0x3dd53b94, v15
	v_mul_f32_e32 v20, v20, v28
	v_cvt_pk_bf16_f32 v15, v15, s0
	global_store_short v[10:11], v15, off offset:2816
	s_waitcnt lgkmcnt(0)
	v_mul_f32_e32 v21, v43, v21
	v_cndmask_b32_e64 v21, v21, -v21, vcc
	v_fmac_f32_e32 v21, v1, v17
	v_mul_f32_e32 v17, 0x3dd53b94, v20
	v_mul_f32_e32 v15, 0x3dd53b94, v21
	v_cvt_pk_bf16_f32 v17, v17, s0
	v_cvt_pk_bf16_f32 v15, v15, s0
	global_store_short v[10:11], v17, off offset:2688
	global_store_short v[10:11], v15, off offset:2944
	global_load_ushort v10, v[12:13], off offset:3584
	s_nop 0
	global_load_ushort v11, v[12:13], off offset:3712
	s_waitcnt vmcnt(1)
	v_lshlrev_b32_e32 v10, 16, v10
	s_waitcnt vmcnt(0)
	v_lshlrev_b32_e32 v11, 16, v11
	v_pk_mul_f32 v[12:13], v[10:11], v[10:11]
	s_nop 0
	v_add_f32_e32 v12, v12, v13
	v_add_f32_e32 v12, v16, v12
	s_nop 1
	v_mov_b32_dpp v13, v12 quad_perm:[1,0,3,2] row_mask:0xf bank_mask:0xf
	s_waitcnt lgkmcnt(0)
	v_add_f32_e32 v12, v12, v13
	s_nop 1
	v_mov_b32_dpp v13, v12 quad_perm:[2,3,0,1] row_mask:0xf bank_mask:0xf
	s_waitcnt lgkmcnt(0)
	v_add_f32_e32 v12, v12, v13
	s_nop 1
	v_mov_b32_dpp v13, v12 row_half_mirror row_mask:0xf bank_mask:0xf
	s_waitcnt lgkmcnt(0)
	v_add_f32_e32 v12, v12, v13
	s_nop 1
	v_mov_b32_dpp v13, v12 row_mirror row_mask:0xf bank_mask:0xf
	s_waitcnt lgkmcnt(0)
	v_add_f32_e32 v12, v12, v13
	v_mov_b32_e32 v13, v12
	s_nop 1
	v_permlane16_swap_b32 v12, v13
	s_waitcnt lgkmcnt(0)
	v_add_f32_e32 v12, v12, v13
	v_mov_b32_e32 v13, v12
	s_nop 1
	v_permlane32_swap_b32 v12, v13
	s_waitcnt lgkmcnt(0)
	v_add_f32_e32 v12, v12, v13
	v_fmamk_f32 v12, v12, 0x3baaaaab, v203
	v_cmp_gt_f32_e64 s[0:1], s71, v12
	v_mul_f32_e32 v13, 0x4b800000, v12
	s_nop 0
	v_cndmask_b32_e64 v12, v12, v13, s[0:1]
	v_rsq_f32_e32 v12, v12
	s_nop 0
	v_mul_f32_e32 v13, 0x45800000, v12
	v_cndmask_b32_e64 v12, v12, v13, s[0:1]
	v_mul_f32_e32 v13, v35, v12
	v_mul_f32_e32 v10, v13, v10
	v_mul_f32_e32 v13, v32, v12
	v_mul_f32_e32 v12, v33, v12
	v_mul_f32_e32 v12, v12, v14
	v_mul_f32_e32 v11, v13, v11
	ds_bpermute_b32 v13, v42, v12
	s_waitcnt lgkmcnt(0)
	v_mul_f32_e32 v13, v43, v13
	v_cndmask_b32_e64 v13, v13, -v13, vcc
	v_fmac_f32_e32 v13, v1, v12
	v_cvt_pk_bf16_f32 v1, v10, s0
	global_store_short v[18:19], v1, off offset:2688
	v_cvt_pk_bf16_f32 v1, v11, s0
	global_store_short v[18:19], v1, off offset:2816
	v_cvt_pk_bf16_f32 v1, v13, s0
	v_cmp_lt_i32_e64 s[0:1], s15, v0
	s_or_b64 s[20:21], s[0:1], s[20:21]
	global_store_short v[18:19], v1, off offset:2944
	s_andn2_b64 exec, exec, s[20:21]
	s_cbranch_execnz .LBB0_202

; __device__ __forceinline__ int opaque_tid() { int t = threadIdx.x; asm volatile("" : "+v"(t)); return t; }
; __device__ __forceinline__ float siluf_(float x) { return x * __builtin_amdgcn_rcpf(1.f + __expf(-x)); }
;     __device__ __forceinline__ void operator()(const f32x4 (&acc)[2][2][4][2], const pg8::Unit& u, int wr, int wc, int fr, int fq) const {
;         const int lane = opaque_tid() & 63;
;         const int src1 = (lane & 48) | ((fr - 1) & 15), src2 = (lane & 48) | ((fr - 2) & 15);
;         const int chb = u.pn * 128 + wc * 32 + 8 * fq;
;         f32x4 w0[2], w1[2], w2[2], bb[2];
; #pragma unroll
;         for (int n = 0; n < 2; ++n) { const int ch0 = chb + 4 * n; w0[n] = *(const f32x4*)(cw + ch0); w1[n] = *(const f32x4*)(cw + DFF + ch0); w2[n] = *(const f32x4*)(cw + 2 * DFF + ch0); bb[n] = *(const f32x4*)(cb + ch0); }
; #pragma unroll
;         for (int ai = 0; ai < 2; ++ai) {
;             const int blk = u.pm * 4 + ai * 2 + wr;
;             float rs[4];
; #pragma unroll
;             for (int m = 0; m < 4; ++m) rs[m] = rsqrtf(ssq[blk * 64 + m * 16 + fr] * (1.f / DM) + EPS);
;             f32x4 p1[2] = {{0.f, 0.f, 0.f, 0.f}, {0.f, 0.f, 0.f, 0.f}}, p2[2] = {{0.f, 0.f, 0.f, 0.f}, {0.f, 0.f, 0.f, 0.f}};
; #pragma unroll
;             for (int m = 0; m < 4; ++m) {
;                 u32x2 gp[2];
; #pragma unroll
;                 for (int n = 0; n < 2; ++n) {
;                     const int ch0 = chb + 4 * n;
;                     const f32x4 av = acc[ai][0][m][n] * rs[m], uv = acc[ai][1][m][n] * rs[m];
;                     f32x4 r1, r2;
; #pragma unroll
;                     for (int j = 0; j < 4; ++j) { r1[j] = __shfl(av[j], src1); r2[j] = __shfl(av[j], src2); }
;                     const f32x4 a1 = fr >= 1 ? r1 : p1[n], a2 = fr >= 2 ? r2 : p2[n];
;                     p1[n] = r1; p2[n] = r2;
;                     const f32x4 c = bb[n] + w0[n] * a2 + w1[n] * a1 + w2[n] * av;
;                     f32x4 g;
; #pragma unroll
;                     for (int j = 0; j < 4; ++j) g[j] = siluf_(c[j]) * uv[j];
;                     gp[n] = pack4(g);
;                     if (m == 3 && fr >= 14) *(f32x4*)(halo + ((size_t)blk * 6 + (fr - 14)) * DFF + ch0) = av;
;                     if (m == 0 && fr < 2) { *(f32x4*)(halo + ((size_t)blk * 6 + 2 + fr) * DFF + ch0) = av; *(f32x4*)(halo + ((size_t)blk * 6 + 4 + fr) * DFF + ch0) = uv; }
.LBB0_315:
	v_lshl_or_b32 v176, s80, 7, v194
	v_ashrrev_i32_e32 v177, 31, v176
	v_lshlrev_b64 v[178:179], 2, v[176:177]
	v_readlane_b32 s48, v255, 58
	v_mov_b32_e32 v182, v202
	v_lshl_add_u64 v[48:49], s[26:27], 0, v[178:179]
	v_readlane_b32 s49, v255, 59
	global_load_dwordx4 v[56:59], v[48:49], off offset:16
	global_load_dwordx4 v[88:91], v[48:49], off
	v_lshl_add_u64 v[48:49], s[48:49], 0, v[178:179]
	v_readlane_b32 s48, v255, 60
	v_readlane_b32 s49, v255, 61
	v_and_b32_e32 v182, 48, v182
	s_lshl_b32 s80, s81, 2
	v_lshl_add_u64 v[64:65], s[48:49], 0, v[178:179]
	v_readlane_b32 s48, v255, 47
	v_and_b32_e32 v183, 64, v208
	s_add_i32 s80, s80, s48
	v_or3_b32 v184, v182, v192, v183
	v_or3_b32 v182, v182, v193, v183
	v_lshlrev_b32_e32 v197, 2, v182
	v_lshl_or_b32 v182, s80, 6, v190
	v_ashrrev_i32_e32 v183, 31, v182
	v_lshl_add_u64 v[92:93], s[6:7], 0, v[178:179]
	v_lshl_add_u64 v[186:187], v[182:183], 2, s[54:55]
	global_load_dwordx4 v[52:55], v[48:49], off offset:16
	global_load_dwordx4 v[84:87], v[48:49], off
	s_nop 0
	global_load_dwordx4 v[48:51], v[64:65], off offset:16
	global_load_dwordx4 v[76:79], v[64:65], off
	s_nop 0
	global_load_dwordx4 v[64:67], v[92:93], off offset:16
	s_nop 0
	global_load_dwordx4 v[92:95], v[92:93], off
	v_lshlrev_b32_e32 v196, 2, v184
	global_load_dword v183, v[186:187], off
	global_load_dword v235, v[186:187], off offset:64
	global_load_dword v226, v[186:187], off offset:128
	global_load_dword v225, v[186:187], off offset:192
	global_load_dword v236, v[186:187], off offset:512
	global_load_dword v237, v[186:187], off offset:576
	global_load_dword v238, v[186:187], off offset:640
	global_load_dword v239, v[186:187], off offset:704
	v_mad_i64_i32 v[186:187], s[48:49], s80, 6, v[168:169]
	s_movk_i32 s81, 0x5800
	v_mad_u64_u32 v[188:189], s[48:49], v186, s81, 0
	v_mov_b32_e32 v186, v189
	v_mad_u64_u32 v[186:187], s[48:49], v187, s81, v[186:187]
	v_mov_b32_e32 v189, v186
	v_mad_i64_i32 v[186:187], s[48:49], s80, 6, v[170:171]
	v_mad_u64_u32 v[198:199], s[48:49], v186, s81, 0
	v_mov_b32_e32 v186, v199
	v_mad_u64_u32 v[186:187], s[48:49], v187, s81, v[186:187]
	v_mov_b32_e32 v199, v186
	v_lshl_add_u64 v[186:187], s[28:29], 0, v[198:199]
	v_lshl_add_u64 v[188:189], s[28:29], 0, v[188:189]
	v_lshl_add_u64 v[186:187], v[186:187], 0, v[178:179]
	v_lshl_add_u64 v[188:189], v[188:189], 0, v[178:179]
	s_waitcnt vmcnt(0)
	v_fmamk_f32 v183, v183, 0x3a000000, v203
	v_cmp_gt_f32_e32 vcc, s71, v183
	v_mul_f32_e32 v184, 0x4b800000, v183
	s_nop 0
	v_cndmask_b32_e32 v183, v183, v184, vcc
	v_rsq_f32_e32 v183, v183
	s_nop 0
	v_mul_f32_e32 v184, 0x45800000, v183
	v_cndmask_b32_e32 v184, v183, v184, vcc
	v_pk_mul_f32 v[158:159], v[158:159], v[184:185] op_sel_hi:[1,0]
	v_pk_mul_f32 v[156:157], v[156:157], v[184:185] op_sel_hi:[1,0]
	s_nop 1
	v_mov_b32_dpp v228, v156 row_ror:1 row_mask:0xf bank_mask:0xf
	v_mov_b32_dpp v227, v156 row_ror:2 row_mask:0xf bank_mask:0xf
	v_mov_b32_dpp v231, v157 row_ror:1 row_mask:0xf bank_mask:0xf
	v_mov_b32_dpp v230, v157 row_ror:2 row_mask:0xf bank_mask:0xf
	v_mov_b32_dpp v233, v158 row_ror:1 row_mask:0xf bank_mask:0xf
	v_mov_b32_dpp v229, v158 row_ror:2 row_mask:0xf bank_mask:0xf
	v_mov_b32_dpp v234, v159 row_ror:1 row_mask:0xf bank_mask:0xf
	v_mov_b32_dpp v232, v159 row_ror:2 row_mask:0xf bank_mask:0xf
	v_pk_mul_f32 v[154:155], v[154:155], v[184:185] op_sel_hi:[1,0]
	v_pk_mul_f32 v[152:153], v[152:153], v[184:185] op_sel_hi:[1,0]
	s_and_saveexec_b64 s[84:85], s[44:45]
	s_cbranch_execz .LBB0_317
	global_store_dwordx4 v[188:189], v[156:159], off
	global_store_dwordx4 v[186:187], v[152:155], off
.LBB0_317:
	s_or_b64 exec, exec, s[84:85]
	v_mov_b32_e32 v185, v184
	v_mov_b32_e32 v214, v184
	v_mov_b32_e32 v215, v184
	v_pk_mul_f32 v[150:151], v[150:151], v[214:215]
	v_pk_mul_f32 v[148:149], v[148:149], v[184:185]
	s_nop 1
	v_mov_b32_dpp v198, v148 row_ror:1 row_mask:0xf bank_mask:0xf
	v_mov_b32_dpp v183, v148 row_ror:2 row_mask:0xf bank_mask:0xf
	v_mov_b32_dpp v201, v149 row_ror:1 row_mask:0xf bank_mask:0xf
	v_mov_b32_dpp v200, v149 row_ror:2 row_mask:0xf bank_mask:0xf
	v_mov_b32_dpp v223, v150 row_ror:1 row_mask:0xf bank_mask:0xf
	v_mov_b32_dpp v199, v150 row_ror:2 row_mask:0xf bank_mask:0xf
	v_mov_b32_dpp v224, v151 row_ror:1 row_mask:0xf bank_mask:0xf
	v_mov_b32_dpp v222, v151 row_ror:2 row_mask:0xf bank_mask:0xf
	v_pk_mul_f32 v[146:147], v[146:147], v[214:215]
	v_pk_mul_f32 v[144:145], v[144:145], v[184:185]
	s_and_saveexec_b64 s[84:85], s[44:45]
	s_cbranch_execz .LBB0_319
	global_store_dwordx4 v[188:189], v[148:151], off offset:16
	global_store_dwordx4 v[186:187], v[144:147], off offset:16

; __device__ __forceinline__ float siluf_(float x) { return x * __builtin_amdgcn_rcpf(1.f + __expf(-x)); }
; __device__ __forceinline__ u32x2 pack4(f32x4 v) { u32x2 r; r.x = cvt_pk_bf16(v[0], v[1]); r.y = cvt_pk_bf16(v[2], v[3]); return r; }
;     __device__ __forceinline__ void operator()(const f32x4 (&acc)[2][2][4][2], const pg8::Unit& u, int wr, int wc, int fr, int fq) const {
;     ...
;             for (int m = 0; m < 4; ++m) rs[m] = rsqrtf(ssq[blk * 64 + m * 16 + fr] * (1.f / DM) + EPS);
;             f32x4 p1[2] = {{0.f, 0.f, 0.f, 0.f}, {0.f, 0.f, 0.f, 0.f}}, p2[2] = {{0.f, 0.f, 0.f, 0.f}, {0.f, 0.f, 0.f, 0.f}};
; #pragma unroll
;             for (int m = 0; m < 4; ++m) {
;                 u32x2 gp[2];
; #pragma unroll
;                 for (int n = 0; n < 2; ++n) {
;                     const int ch0 = chb + 4 * n;
;                     const f32x4 av = acc[ai][0][m][n] * rs[m], uv = acc[ai][1][m][n] * rs[m];
;                     f32x4 r1, r2;
; #pragma unroll
;                     for (int j = 0; j < 4; ++j) { r1[j] = __shfl(av[j], src1); r2[j] = __shfl(av[j], src2); }
;                     const f32x4 a1 = fr >= 1 ? r1 : p1[n], a2 = fr >= 2 ? r2 : p2[n];
;                     p1[n] = r1; p2[n] = r2;
;                     const f32x4 c = bb[n] + w0[n] * a2 + w1[n] * a1 + w2[n] * av;
;                     f32x4 g;
; #pragma unroll
;                     for (int j = 0; j < 4; ++j) g[j] = siluf_(c[j]) * uv[j];
;                     gp[n] = pack4(g);
;                     if (m == 3 && fr >= 14) *(f32x4*)(halo + ((size_t)blk * 6 + (fr - 14)) * DFF + ch0) = av;
;                     if (m == 0 && fr < 2) { *(f32x4*)(halo + ((size_t)blk * 6 + 2 + fr) * DFF + ch0) = av; *(f32x4*)(halo + ((size_t)blk * 6 + 4 + fr) * DFF + ch0) = uv; }
;                 }
;                 const int row = blk * 64 + m * 16 + fr;
;                 if (m > 0 || fr >= 2) { const u32x4 gw = {gp[0].x, gp[0].y, gp[1].x, gp[1].y}; *(u32x4*)(G + (size_t)row * DFF + chb) = gw; }
.LBB0_321:
	s_or_b64 exec, exec, s[84:85]
	v_fmamk_f32 v144, v235, 0x3a000000, v203
	v_cmp_gt_f32_e32 vcc, s71, v144
	v_mul_f32_e32 v145, 0x4b800000, v144
	s_mul_hi_i32 s49, s80, 6
	v_cndmask_b32_e32 v144, v144, v145, vcc
	v_rsq_f32_e32 v144, v144
	s_mul_i32 s48, s80, 6
	v_lshl_add_u64 v[152:153], s[48:49], 0, v[166:167]
	v_or_b32_e32 v149, 16, v182
	v_mul_f32_e32 v145, 0x45800000, v144
	v_cndmask_b32_e32 v150, v144, v145, vcc
	v_fmamk_f32 v144, v226, 0x3a000000, v203
	v_cmp_gt_f32_e32 vcc, s71, v144
	v_mul_f32_e32 v146, 0x4b800000, v144
	v_pk_mul_f32 v[140:141], v[140:141], v[150:151] op_sel_hi:[1,0]
	v_cndmask_b32_e32 v144, v144, v146, vcc
	v_rsq_f32_e32 v144, v144
	s_nop 1
	v_mov_b32_dpp v185, v140 row_ror:2 row_mask:0xf bank_mask:0xf
	v_mov_b32_dpp v187, v141 row_ror:2 row_mask:0xf bank_mask:0xf
	v_mov_b32_dpp v184, v140 row_ror:1 row_mask:0xf bank_mask:0xf
	v_mul_f32_e32 v146, 0x45800000, v144
	s_nop 1
	v_mov_b32_dpp v186, v141 row_ror:1 row_mask:0xf bank_mask:0xf
	v_cndmask_b32_e32 v148, v144, v146, vcc
	v_fmamk_f32 v144, v225, 0x3a000000, v203
	v_cmp_gt_f32_e32 vcc, s71, v144
	v_mul_f32_e32 v146, 0x4b800000, v144
	s_waitcnt lgkmcnt(0)
	v_cndmask_b32_e64 v157, v230, v187, s[40:41]
	v_cndmask_b32_e32 v144, v144, v146, vcc
	v_rsq_f32_e32 v144, v144
	v_cndmask_b32_e64 v156, v227, v185, s[40:41]
	v_pk_mul_f32 v[142:143], v[142:143], v[150:151] op_sel_hi:[1,0]
	v_cndmask_b32_e64 v155, v186, v231, s[38:39]
	v_cndmask_b32_e64 v154, v184, v228, s[38:39]
	v_pk_fma_f32 v[156:157], v[88:89], v[156:157], v[92:93]
	s_nop 1
	v_mov_b32_dpp v189, v142 row_ror:2 row_mask:0xf bank_mask:0xf
	v_mov_b32_dpp v215, v143 row_ror:2 row_mask:0xf bank_mask:0xf
	v_pk_fma_f32 v[154:155], v[84:85], v[154:155], v[156:157]
	s_nop 1
	v_mov_b32_dpp v188, v142 row_ror:1 row_mask:0xf bank_mask:0xf
	v_mov_b32_dpp v214, v143 row_ror:1 row_mask:0xf bank_mask:0xf
	v_pk_fma_f32 v[140:141], v[76:77], v[140:141], v[154:155]
	v_mul_f32_e32 v146, 0x45800000, v144
	v_pk_mul_f32 v[138:139], v[138:139], v[150:151] op_sel_hi:[1,0]
	v_pk_mul_f32 v[136:137], v[136:137], v[150:151] op_sel_hi:[1,0]
	v_mul_f32_e32 v151, 0xbfb8aa3b, v140
	v_cndmask_b32_e32 v144, v144, v146, vcc
	v_mad_u64_u32 v[146:147], s[48:49], v152, s81, 0
	v_exp_f32_e32 v151, v151
	v_mov_b32_e32 v152, v147
	v_mad_u64_u32 v[152:153], s[48:49], v153, s81, v[152:153]
	s_waitcnt lgkmcnt(2)
	v_cndmask_b32_e64 v159, v232, v215, s[40:41]
	v_cndmask_b32_e64 v158, v229, v189, s[40:41]
	v_mov_b32_e32 v147, v152
	s_waitcnt lgkmcnt(0)
	v_cndmask_b32_e64 v153, v214, v234, s[38:39]
	v_cndmask_b32_e64 v152, v188, v233, s[38:39]
	v_pk_fma_f32 v[158:159], v[90:91], v[158:159], v[94:95]
	v_add_f32_e32 v151, 1.0, v151
	v_pk_fma_f32 v[152:153], v[86:87], v[152:153], v[158:159]
	v_pk_mul_f32 v[120:121], v[120:121], v[148:149] op_sel_hi:[1,0]
	v_pk_fma_f32 v[142:143], v[78:79], v[142:143], v[152:153]
	v_rcp_f32_e32 v152, v151
	v_mul_f32_e32 v151, 0xbfb8aa3b, v141
	v_exp_f32_e32 v151, v151
	v_pk_mul_f32 v[122:123], v[122:123], v[148:149] op_sel_hi:[1,0]
	v_pk_mul_f32 v[114:115], v[114:115], v[148:149] op_sel_hi:[1,0]
	v_pk_mul_f32 v[112:113], v[112:113], v[148:149] op_sel_hi:[1,0]
	v_add_f32_e32 v151, 1.0, v151
	v_rcp_f32_e32 v153, v151
	v_pk_mul_f32 v[132:133], v[132:133], v[150:151] op_sel_hi:[1,0]
	v_pk_mul_f32 v[134:135], v[134:135], v[150:151] op_sel_hi:[1,0]
	s_nop 1
	v_mov_b32_dpp v155, v132 row_ror:2 row_mask:0xf bank_mask:0xf
	v_pk_mul_f32 v[140:141], v[140:141], v[152:153]
	s_nop 1
	v_mov_b32_dpp v157, v133 row_ror:2 row_mask:0xf bank_mask:0xf
	v_pk_mul_f32 v[136:137], v[136:137], v[140:141]
	v_mul_f32_e32 v140, 0xbfb8aa3b, v142
	v_mul_f32_e32 v141, 0xbfb8aa3b, v143
	v_exp_f32_e32 v140, v140
	v_exp_f32_e32 v141, v141
	s_nop 1
	v_mov_b32_dpp v154, v132 row_ror:1 row_mask:0xf bank_mask:0xf
	v_mov_b32_dpp v156, v133 row_ror:1 row_mask:0xf bank_mask:0xf
	v_add_f32_e32 v140, 1.0, v140
	v_add_f32_e32 v141, 1.0, v141
	v_rcp_f32_e32 v140, v140
	v_rcp_f32_e32 v141, v141
	s_nop 1
	v_mov_b32_dpp v159, v134 row_ror:2 row_mask:0xf bank_mask:0xf
	v_mov_b32_dpp v217, v135 row_ror:2 row_mask:0xf bank_mask:0xf
	v_mov_b32_dpp v158, v134 row_ror:1 row_mask:0xf bank_mask:0xf
	v_mov_b32_dpp v216, v135 row_ror:1 row_mask:0xf bank_mask:0xf
	v_pk_mul_f32 v[140:141], v[142:143], v[140:141]
	s_waitcnt lgkmcnt(6)
	v_cndmask_b32_e64 v143, v200, v157, s[40:41]
	v_cndmask_b32_e64 v142, v183, v155, s[40:41]
	v_pk_mul_f32 v[138:139], v[138:139], v[140:141]
	v_pk_mul_f32 v[130:131], v[130:131], v[150:151] op_sel_hi:[1,0]
	v_pk_mul_f32 v[128:129], v[128:129], v[150:151] op_sel_hi:[1,0]
	s_waitcnt lgkmcnt(4)
	v_cndmask_b32_e64 v141, v156, v201, s[38:39]
	v_cndmask_b32_e64 v140, v154, v198, s[38:39]
	s_waitcnt lgkmcnt(2)
	v_cndmask_b32_e64 v151, v222, v217, s[40:41]
	v_cndmask_b32_e64 v150, v199, v159, s[40:41]
	v_pk_fma_f32 v[142:143], v[56:57], v[142:143], v[64:65]
	v_cvt_pk_bf16_f32 v136, v136, v137
	v_cvt_pk_bf16_f32 v137, v138, v139
	s_waitcnt lgkmcnt(0)
; __device__ __forceinline__ float siluf_(float x) { return x * __builtin_amdgcn_rcpf(1.f + __expf(-x)); }
; __device__ __forceinline__ u32x2 pack4(f32x4 v) { u32x2 r; r.x = cvt_pk_bf16(v[0], v[1]); r.y = cvt_pk_bf16(v[2], v[3]); return r; }
;     __device__ __forceinline__ void operator()(const f32x4 (&acc)[2][2][4][2], const pg8::Unit& u, int wr, int wc, int fr, int fq) const {
;     ...
;             for (int m = 0; m < 4; ++m) {
;                 u32x2 gp[2];
; #pragma unroll
;                 for (int n = 0; n < 2; ++n) {
;                     const int ch0 = chb + 4 * n;
;                     const f32x4 av = acc[ai][0][m][n] * rs[m], uv = acc[ai][1][m][n] * rs[m];
;                     f32x4 r1, r2;
; #pragma unroll
;                     for (int j = 0; j < 4; ++j) { r1[j] = __shfl(av[j], src1); r2[j] = __shfl(av[j], src2); }
;                     const f32x4 a1 = fr >= 1 ? r1 : p1[n], a2 = fr >= 2 ? r2 : p2[n];
;                     p1[n] = r1; p2[n] = r2;
;                     const f32x4 c = bb[n] + w0[n] * a2 + w1[n] * a1 + w2[n] * av;
;                     f32x4 g;
; #pragma unroll
;                     for (int j = 0; j < 4; ++j) g[j] = siluf_(c[j]) * uv[j];
;                     gp[n] = pack4(g);
;                     if (m == 3 && fr >= 14) *(f32x4*)(halo + ((size_t)blk * 6 + (fr - 14)) * DFF + ch0) = av;
;                     if (m == 0 && fr < 2) { *(f32x4*)(halo + ((size_t)blk * 6 + 2 + fr) * DFF + ch0) = av; *(f32x4*)(halo + ((size_t)blk * 6 + 4 + fr) * DFF + ch0) = uv; }
;                 }
;                 const int row = blk * 64 + m * 16 + fr;
;                 if (m > 0 || fr >= 2) { const u32x4 gw = {gp[0].x, gp[0].y, gp[1].x, gp[1].y}; *(u32x4*)(G + (size_t)row * DFF + chb) = gw; }
	v_cndmask_b32_e64 v139, v216, v224, s[38:39]
	v_cndmask_b32_e64 v138, v158, v223, s[38:39]
	v_pk_fma_f32 v[150:151], v[58:59], v[150:151], v[66:67]
	v_pk_fma_f32 v[140:141], v[52:53], v[140:141], v[142:143]
	v_pk_fma_f32 v[138:139], v[54:55], v[138:139], v[150:151]
	v_pk_fma_f32 v[132:133], v[48:49], v[132:133], v[140:141]
	v_pk_fma_f32 v[134:135], v[50:51], v[134:135], v[138:139]
	v_mul_f32_e32 v138, 0xbfb8aa3b, v132
	v_mul_f32_e32 v139, 0xbfb8aa3b, v133
	v_exp_f32_e32 v138, v138
	v_exp_f32_e32 v139, v139
	v_or_b32_e32 v145, 32, v182
	v_pk_mul_f32 v[110:111], v[110:111], v[144:145] op_sel_hi:[1,0]
	v_add_f32_e32 v138, 1.0, v138
	v_add_f32_e32 v139, 1.0, v139
	v_rcp_f32_e32 v138, v138
	v_rcp_f32_e32 v139, v139
	v_pk_mul_f32 v[108:109], v[108:109], v[144:145] op_sel_hi:[1,0]
	v_pk_mul_f32 v[132:133], v[132:133], v[138:139]
	s_nop 0
	v_pk_mul_f32 v[128:129], v[128:129], v[132:133]
	v_mul_f32_e32 v132, 0xbfb8aa3b, v134
	v_mul_f32_e32 v133, 0xbfb8aa3b, v135
	v_exp_f32_e32 v132, v132
	v_exp_f32_e32 v133, v133
	v_cvt_pk_bf16_f32 v138, v128, v129
	v_lshlrev_b64 v[128:129], 1, v[176:177]
	v_add_f32_e32 v132, 1.0, v132
	v_add_f32_e32 v133, 1.0, v133
	v_rcp_f32_e32 v132, v132
	v_rcp_f32_e32 v133, v133
	s_nop 0
	v_pk_mul_f32 v[132:133], v[134:135], v[132:133]
	s_nop 0
	v_pk_mul_f32 v[130:131], v[130:131], v[132:133]
	s_nop 0
	v_cvt_pk_bf16_f32 v139, v130, v131
	v_mov_b64_e32 v[130:131], s[14:15]
	v_mad_i64_i32 v[132:133], s[48:49], v149, s86, v[130:131]
	v_lshl_add_u64 v[132:133], v[132:133], 0, v[128:129]
	global_store_dwordx4 v[132:133], v[136:139], off
	s_nop 1
	v_pk_mul_f32 v[138:139], v[124:125], v[148:149] op_sel_hi:[1,0]
	v_pk_mul_f32 v[136:137], v[126:127], v[148:149] op_sel_hi:[1,0]
	s_nop 1
	v_mov_b32_dpp v124, v138 row_ror:2 row_mask:0xf bank_mask:0xf
	v_mov_b32_dpp v127, v139 row_ror:2 row_mask:0xf bank_mask:0xf
	v_mov_b32_dpp v125, v138 row_ror:1 row_mask:0xf bank_mask:0xf
	v_mov_b32_dpp v132, v139 row_ror:1 row_mask:0xf bank_mask:0xf
	v_mov_b32_dpp v126, v136 row_ror:2 row_mask:0xf bank_mask:0xf
	v_mov_b32_dpp v135, v137 row_ror:2 row_mask:0xf bank_mask:0xf
	v_mov_b32_dpp v133, v136 row_ror:1 row_mask:0xf bank_mask:0xf
	v_mov_b32_dpp v134, v137 row_ror:1 row_mask:0xf bank_mask:0xf
	s_waitcnt lgkmcnt(6)
	v_cndmask_b32_e64 v151, v187, v127, s[40:41]
	v_cndmask_b32_e64 v150, v185, v124, s[40:41]
	s_waitcnt lgkmcnt(4)
	v_cndmask_b32_e64 v143, v132, v186, s[38:39]
	v_cndmask_b32_e64 v142, v125, v184, s[38:39]
	s_waitcnt lgkmcnt(2)
	v_cndmask_b32_e64 v153, v215, v135, s[40:41]
	v_cndmask_b32_e64 v152, v189, v126, s[40:41]
	v_pk_fma_f32 v[150:151], v[88:89], v[150:151], v[92:93]
	s_waitcnt lgkmcnt(0)
	v_cndmask_b32_e64 v141, v134, v214, s[38:39]
	v_cndmask_b32_e64 v140, v133, v188, s[38:39]
	v_pk_fma_f32 v[152:153], v[90:91], v[152:153], v[94:95]
	v_pk_fma_f32 v[142:143], v[84:85], v[142:143], v[150:151]
	v_pk_fma_f32 v[140:141], v[86:87], v[140:141], v[152:153]
	v_pk_fma_f32 v[138:139], v[76:77], v[138:139], v[142:143]
	v_pk_fma_f32 v[136:137], v[78:79], v[136:137], v[140:141]
	v_mul_f32_e32 v140, 0xbfb8aa3b, v138
	v_mul_f32_e32 v141, 0xbfb8aa3b, v139
	v_exp_f32_e32 v140, v140
	v_exp_f32_e32 v141, v141
	v_add_f32_e32 v140, 1.0, v140
	v_add_f32_e32 v141, 1.0, v141
	v_rcp_f32_e32 v140, v140
	v_rcp_f32_e32 v141, v141
	s_nop 0
	v_pk_mul_f32 v[138:139], v[138:139], v[140:141]
	s_nop 0
	v_pk_mul_f32 v[120:121], v[120:121], v[138:139]
	v_mul_f32_e32 v138, 0xbfb8aa3b, v136
	v_mul_f32_e32 v139, 0xbfb8aa3b, v137
	v_exp_f32_e32 v138, v138
	v_exp_f32_e32 v139, v139
	v_pk_mul_f32 v[140:141], v[116:117], v[148:149] op_sel_hi:[1,0]
	s_nop 1
	v_mov_b32_dpp v116, v140 row_ror:2 row_mask:0xf bank_mask:0xf
	v_add_f32_e32 v138, 1.0, v138
	v_add_f32_e32 v139, 1.0, v139
	v_rcp_f32_e32 v138, v138
	v_rcp_f32_e32 v139, v139
	s_nop 1
	v_mov_b32_dpp v117, v140 row_ror:1 row_mask:0xf bank_mask:0xf
	s_waitcnt lgkmcnt(1)
	v_cndmask_b32_e64 v150, v155, v116, s[40:41]
	v_pk_mul_f32 v[136:137], v[136:137], v[138:139]
	s_nop 0
	v_pk_mul_f32 v[122:123], v[122:123], v[136:137]
	v_pk_mul_f32 v[138:139], v[118:119], v[148:149] op_sel_hi:[1,0]
	s_nop 1
	v_mov_b32_dpp v119, v141 row_ror:2 row_mask:0xf bank_mask:0xf
	v_cvt_pk_bf16_f32 v136, v120, v121
	v_cvt_pk_bf16_f32 v137, v122, v123
	s_nop 1
	v_mov_b32_dpp v120, v141 row_ror:1 row_mask:0xf bank_mask:0xf
	v_mov_b32_dpp v118, v138 row_ror:2 row_mask:0xf bank_mask:0xf
	v_mov_b32_dpp v123, v139 row_ror:2 row_mask:0xf bank_mask:0xf
	v_mov_b32_dpp v121, v138 row_ror:1 row_mask:0xf bank_mask:0xf
	v_mov_b32_dpp v122, v139 row_ror:1 row_mask:0xf bank_mask:0xf
	s_waitcnt lgkmcnt(5)
	v_cndmask_b32_e64 v151, v157, v119, s[40:41]
	s_waitcnt lgkmcnt(4)
	v_cndmask_b32_e64 v149, v120, v156, s[38:39]
	v_cndmask_b32_e64 v148, v117, v154, s[38:39]
	s_waitcnt lgkmcnt(2)
	v_cndmask_b32_e64 v153, v217, v123, s[40:41]
	v_cndmask_b32_e64 v152, v159, v118, s[40:41]
	v_pk_fma_f32 v[150:151], v[56:57], v[150:151], v[64:65]
	s_waitcnt lgkmcnt(0)
	v_cndmask_b32_e64 v143, v122, v216, s[38:39]
	v_cndmask_b32_e64 v142, v121, v158, s[38:39]
	v_pk_fma_f32 v[152:153], v[58:59], v[152:153], v[66:67]
	v_pk_fma_f32 v[148:149], v[52:53], v[148:149], v[150:151]
	v_pk_fma_f32 v[142:143], v[54:55], v[142:143], v[152:153]
	v_pk_fma_f32 v[140:141], v[48:49], v[140:141], v[148:149]
	v_pk_fma_f32 v[138:139], v[50:51], v[138:139], v[142:143]
	v_mul_f32_e32 v142, 0xbfb8aa3b, v140
	v_mul_f32_e32 v143, 0xbfb8aa3b, v141
	v_exp_f32_e32 v142, v142
	v_exp_f32_e32 v143, v143
	s_nop 1
	v_mov_b32_dpp v150, v109 row_ror:1 row_mask:0xf bank_mask:0xf
	v_mov_b32_dpp v149, v109 row_ror:2 row_mask:0xf bank_mask:0xf
	v_add_f32_e32 v142, 1.0, v142
	v_add_f32_e32 v143, 1.0, v143
	v_rcp_f32_e32 v142, v142
	v_rcp_f32_e32 v143, v143
	s_nop 1
	v_mov_b32_dpp v152, v110 row_ror:1 row_mask:0xf bank_mask:0xf
	v_mov_b32_dpp v148, v110 row_ror:2 row_mask:0xf bank_mask:0xf
	v_mov_b32_dpp v153, v111 row_ror:1 row_mask:0xf bank_mask:0xf
	v_pk_mul_f32 v[140:141], v[140:141], v[142:143]
	s_nop 1
	v_mov_b32_dpp v143, v108 row_ror:1 row_mask:0xf bank_mask:0xf
	v_pk_mul_f32 v[112:113], v[112:113], v[140:141]
	v_mul_f32_e32 v140, 0xbfb8aa3b, v138
	v_mul_f32_e32 v141, 0xbfb8aa3b, v139
	v_exp_f32_e32 v140, v140
	v_exp_f32_e32 v141, v141
	s_nop 1
	v_mov_b32_dpp v142, v108 row_ror:2 row_mask:0xf bank_mask:0xf
	v_mov_b32_dpp v151, v111 row_ror:2 row_mask:0xf bank_mask:0xf
	v_add_f32_e32 v140, 1.0, v140
	v_add_f32_e32 v141, 1.0, v141
	v_rcp_f32_e32 v140, v140
	v_rcp_f32_e32 v141, v141
	s_nop 0
	v_pk_mul_f32 v[138:139], v[138:139], v[140:141]
	s_nop 0
	v_pk_mul_f32 v[114:115], v[114:115], v[138:139]
	v_cvt_pk_bf16_f32 v138, v112, v113
	v_mad_i64_i32 v[112:113], s[48:49], v145, s86, v[130:131]
	v_cvt_pk_bf16_f32 v139, v114, v115
	v_lshl_add_u64 v[112:113], v[112:113], 0, v[128:129]
	global_store_dwordx4 v[112:113], v[136:139], off
	v_lshl_add_u64 v[112:113], s[28:29], 0, v[146:147]
	v_lshl_add_u64 v[114:115], v[176:177], 2, v[112:113]
	s_and_saveexec_b64 s[84:85], s[42:43]
	s_cbranch_execz .LBB0_323
	global_store_dwordx4 v[114:115], v[108:111], off
; __device__ __forceinline__ float siluf_(float x) { return x * __builtin_amdgcn_rcpf(1.f + __expf(-x)); }
; __device__ __forceinline__ u32x2 pack4(f32x4 v) { u32x2 r; r.x = cvt_pk_bf16(v[0], v[1]); r.y = cvt_pk_bf16(v[2], v[3]); return r; }
;     __device__ __forceinline__ void operator()(const f32x4 (&acc)[2][2][4][2], const pg8::Unit& u, int wr, int wc, int fr, int fq) const {
;     ...
;         for (int ai = 0; ai < 2; ++ai) {
;             const int blk = u.pm * 4 + ai * 2 + wr;
;             float rs[4];
; #pragma unroll
;             for (int m = 0; m < 4; ++m) rs[m] = rsqrtf(ssq[blk * 64 + m * 16 + fr] * (1.f / DM) + EPS);
;             f32x4 p1[2] = {{0.f, 0.f, 0.f, 0.f}, {0.f, 0.f, 0.f, 0.f}}, p2[2] = {{0.f, 0.f, 0.f, 0.f}, {0.f, 0.f, 0.f, 0.f}};
; #pragma unroll
;             for (int m = 0; m < 4; ++m) {
;                 u32x2 gp[2];
; #pragma unroll
;                 for (int n = 0; n < 2; ++n) {
;                     const int ch0 = chb + 4 * n;
;                     const f32x4 av = acc[ai][0][m][n] * rs[m], uv = acc[ai][1][m][n] * rs[m];
;                     f32x4 r1, r2;
; #pragma unroll
;                     for (int j = 0; j < 4; ++j) { r1[j] = __shfl(av[j], src1); r2[j] = __shfl(av[j], src2); }
;                     const f32x4 a1 = fr >= 1 ? r1 : p1[n], a2 = fr >= 2 ? r2 : p2[n];
;                     p1[n] = r1; p2[n] = r2;
;                     const f32x4 c = bb[n] + w0[n] * a2 + w1[n] * a1 + w2[n] * av;
;                     f32x4 g;
; #pragma unroll
;                     for (int j = 0; j < 4; ++j) g[j] = siluf_(c[j]) * uv[j];
;                     gp[n] = pack4(g);
;                     if (m == 3 && fr >= 14) *(f32x4*)(halo + ((size_t)blk * 6 + (fr - 14)) * DFF + ch0) = av;
;                     if (m == 0 && fr < 2) { *(f32x4*)(halo + ((size_t)blk * 6 + 2 + fr) * DFF + ch0) = av; *(f32x4*)(halo + ((size_t)blk * 6 + 4 + fr) * DFF + ch0) = uv; }
;                 }
;                 const int row = blk * 64 + m * 16 + fr;
;                 if (m > 0 || fr >= 2) { const u32x4 gw = {gp[0].x, gp[0].y, gp[1].x, gp[1].y}; *(u32x4*)(G + (size_t)row * DFF + chb) = gw; }
.LBB0_323:
	s_or_b64 exec, exec, s[84:85]
	v_mov_b32_e32 v145, v144
	v_mov_b32_e32 v112, v144
	v_mov_b32_e32 v113, v144
	v_pk_mul_f32 v[106:107], v[106:107], v[112:113]
	v_pk_mul_f32 v[104:105], v[104:105], v[144:145]
	s_nop 1
	v_mov_b32_dpp v131, v104 row_ror:1 row_mask:0xf bank_mask:0xf
	v_mov_b32_dpp v130, v104 row_ror:2 row_mask:0xf bank_mask:0xf
	v_mov_b32_dpp v138, v105 row_ror:1 row_mask:0xf bank_mask:0xf
	v_mov_b32_dpp v137, v105 row_ror:2 row_mask:0xf bank_mask:0xf
	v_mov_b32_dpp v140, v106 row_ror:1 row_mask:0xf bank_mask:0xf
	v_mov_b32_dpp v136, v106 row_ror:2 row_mask:0xf bank_mask:0xf
	v_mov_b32_dpp v141, v107 row_ror:1 row_mask:0xf bank_mask:0xf
	v_mov_b32_dpp v139, v107 row_ror:2 row_mask:0xf bank_mask:0xf
	s_and_saveexec_b64 s[84:85], s[42:43]
	s_cbranch_execz .LBB0_325
	global_store_dwordx4 v[114:115], v[104:107], off offset:16
.LBB0_325:
	s_or_b64 exec, exec, s[84:85]
	s_waitcnt lgkmcnt(13)
	v_cndmask_b32_e64 v114, v152, v133, s[38:39]
	v_cndmask_b32_e64 v133, v150, v132, s[38:39]
	s_waitcnt lgkmcnt(10)
	v_cndmask_b32_e64 v132, v143, v125, s[38:39]
	v_cndmask_b32_e64 v125, v127, v149, s[40:41]
	s_waitcnt lgkmcnt(9)
	v_cndmask_b32_e64 v124, v124, v142, s[40:41]
	s_waitcnt lgkmcnt(8)
	v_cndmask_b32_e64 v127, v135, v151, s[40:41]
	v_cndmask_b32_e64 v126, v126, v148, s[40:41]
	v_pk_fma_f32 v[124:125], v[88:89], v[124:125], v[92:93]
	v_cndmask_b32_e64 v115, v153, v134, s[38:39]
	v_pk_fma_f32 v[126:127], v[90:91], v[126:127], v[94:95]
	v_pk_fma_f32 v[124:125], v[84:85], v[132:133], v[124:125]
	v_pk_fma_f32 v[114:115], v[86:87], v[114:115], v[126:127]
	v_pk_fma_f32 v[108:109], v[76:77], v[108:109], v[124:125]
	v_pk_fma_f32 v[110:111], v[78:79], v[110:111], v[114:115]
	v_mul_f32_e32 v114, 0xbfb8aa3b, v108
	v_mul_f32_e32 v115, 0xbfb8aa3b, v109
	v_exp_f32_e32 v114, v114
	v_exp_f32_e32 v115, v115
	v_pk_mul_f32 v[100:101], v[100:101], v[144:145]
	v_pk_mul_f32 v[102:103], v[102:103], v[112:113]
	v_add_f32_e32 v114, 1.0, v114
	v_add_f32_e32 v115, 1.0, v115
	v_rcp_f32_e32 v114, v114
	v_rcp_f32_e32 v115, v115
	v_pk_mul_f32 v[98:99], v[98:99], v[112:113]
	s_waitcnt lgkmcnt(0)
	v_cndmask_b32_e64 v113, v123, v139, s[40:41]
	v_cndmask_b32_e64 v112, v118, v136, s[40:41]
	v_pk_mul_f32 v[108:109], v[108:109], v[114:115]
	v_pk_fma_f32 v[112:113], v[58:59], v[112:113], v[66:67]
	v_pk_mul_f32 v[100:101], v[100:101], v[108:109]
	v_mul_f32_e32 v108, 0xbfb8aa3b, v110
	v_mul_f32_e32 v109, 0xbfb8aa3b, v111
	v_exp_f32_e32 v108, v108
	v_exp_f32_e32 v109, v109
	v_cvt_pk_bf16_f32 v100, v100, v101
	v_pk_mul_f32 v[96:97], v[96:97], v[144:145]
	v_add_f32_e32 v108, 1.0, v108
	v_add_f32_e32 v109, 1.0, v109
	v_rcp_f32_e32 v108, v108
	v_rcp_f32_e32 v109, v109
	s_add_i32 s80, s80, 2
	v_pk_mul_f32 v[108:109], v[110:111], v[108:109]
	v_cndmask_b32_e64 v111, v119, v137, s[40:41]
	v_cndmask_b32_e64 v110, v116, v130, s[40:41]
	v_pk_mul_f32 v[102:103], v[102:103], v[108:109]
	v_cndmask_b32_e64 v109, v138, v120, s[38:39]
	v_cndmask_b32_e64 v108, v131, v117, s[38:39]
	v_pk_fma_f32 v[110:111], v[56:57], v[110:111], v[64:65]
	v_cvt_pk_bf16_f32 v101, v102, v103
	v_cndmask_b32_e64 v103, v141, v122, s[38:39]
	v_cndmask_b32_e64 v102, v140, v121, s[38:39]
	v_pk_fma_f32 v[108:109], v[52:53], v[108:109], v[110:111]
	v_pk_fma_f32 v[102:103], v[54:55], v[102:103], v[112:113]
	v_pk_fma_f32 v[104:105], v[48:49], v[104:105], v[108:109]
	v_pk_fma_f32 v[102:103], v[50:51], v[106:107], v[102:103]
	v_mul_f32_e32 v106, 0xbfb8aa3b, v104
	v_mul_f32_e32 v107, 0xbfb8aa3b, v105
	v_exp_f32_e32 v106, v106
	v_exp_f32_e32 v107, v107
	v_add_f32_e32 v106, 1.0, v106
	v_add_f32_e32 v107, 1.0, v107
	v_rcp_f32_e32 v106, v106
	v_rcp_f32_e32 v107, v107
	s_nop 0
	v_pk_mul_f32 v[104:105], v[104:105], v[106:107]
	s_nop 0
	v_pk_mul_f32 v[96:97], v[96:97], v[104:105]
	v_mul_f32_e32 v104, 0xbfb8aa3b, v102
	v_mul_f32_e32 v105, 0xbfb8aa3b, v103
	v_exp_f32_e32 v104, v104
	v_exp_f32_e32 v105, v105
	v_add_f32_e32 v104, 1.0, v104
	v_add_f32_e32 v105, 1.0, v105
	v_rcp_f32_e32 v104, v104
	v_rcp_f32_e32 v105, v105
	s_nop 0
	v_pk_mul_f32 v[102:103], v[102:103], v[104:105]
	s_nop 0
	v_pk_mul_f32 v[98:99], v[98:99], v[102:103]
	v_cvt_pk_bf16_f32 v102, v96, v97
	v_cvt_pk_bf16_f32 v103, v98, v99
	v_or_b32_e32 v98, 48, v182
	v_mov_b64_e32 v[96:97], s[14:15]
	v_mad_i64_i32 v[96:97], s[48:49], v98, s86, v[96:97]
	v_lshl_add_u64 v[96:97], v[176:177], 1, v[96:97]
	global_store_dwordx4 v[96:97], v[100:103], off
	v_lshl_or_b32 v96, s80, 6, v190
	v_ashrrev_i32_e32 v97, 31, v96
	v_lshl_add_u64 v[100:101], v[96:97], 2, s[54:55]
	v_mov_b32_e32 v97, v236
	v_mov_b32_e32 v121, v237
	v_mov_b32_e32 v119, v238
	v_mov_b32_e32 v111, v239
	v_mad_i64_i32 v[100:101], s[48:49], s80, 6, v[168:169]
	v_mad_u64_u32 v[102:103], s[48:49], v100, s81, 0
	v_mov_b32_e32 v100, v103
	v_mad_u64_u32 v[100:101], s[48:49], v101, s81, v[100:101]
	v_mov_b32_e32 v103, v100
	v_mad_i64_i32 v[100:101], s[48:49], s80, 6, v[170:171]
	v_mad_u64_u32 v[104:105], s[48:49], v100, s81, 0
	v_mov_b32_e32 v100, v105
	v_mad_u64_u32 v[100:101], s[48:49], v101, s81, v[100:101]
	v_mov_b32_e32 v105, v100
	v_lshl_add_u64 v[100:101], s[28:29], 0, v[104:105]
	v_lshl_add_u64 v[102:103], s[28:29], 0, v[102:103]
	v_lshl_add_u64 v[100:101], v[100:101], 0, v[178:179]
	v_lshl_add_u64 v[102:103], v[102:103], 0, v[178:179]
	v_fmamk_f32 v97, v97, 0x3a000000, v203
	v_cmp_gt_f32_e32 vcc, s71, v97
	v_mul_f32_e32 v98, 0x4b800000, v97
	s_nop 0
	v_cndmask_b32_e32 v97, v97, v98, vcc
	v_rsq_f32_e32 v97, v97
	s_nop 0
	v_mul_f32_e32 v98, 0x45800000, v97
	v_cndmask_b32_e32 v98, v97, v98, vcc
	v_pk_mul_f32 v[82:83], v[82:83], v[98:99] op_sel_hi:[1,0]
	v_pk_mul_f32 v[80:81], v[80:81], v[98:99] op_sel_hi:[1,0]
	s_nop 1
	v_mov_b32_dpp v113, v80 row_ror:1 row_mask:0xf bank_mask:0xf
	v_mov_b32_dpp v112, v80 row_ror:2 row_mask:0xf bank_mask:0xf
	v_mov_b32_dpp v116, v81 row_ror:1 row_mask:0xf bank_mask:0xf
	v_mov_b32_dpp v115, v81 row_ror:2 row_mask:0xf bank_mask:0xf
	v_mov_b32_dpp v118, v82 row_ror:1 row_mask:0xf bank_mask:0xf
	v_mov_b32_dpp v114, v82 row_ror:2 row_mask:0xf bank_mask:0xf
	v_mov_b32_dpp v120, v83 row_ror:1 row_mask:0xf bank_mask:0xf
	v_mov_b32_dpp v117, v83 row_ror:2 row_mask:0xf bank_mask:0xf
	v_pk_mul_f32 v[74:75], v[74:75], v[98:99] op_sel_hi:[1,0]
	v_pk_mul_f32 v[72:73], v[72:73], v[98:99] op_sel_hi:[1,0]
	s_and_saveexec_b64 s[84:85], s[44:45]
	s_cbranch_execz .LBB0_327
	global_store_dwordx4 v[102:103], v[80:83], off
	global_store_dwordx4 v[100:101], v[72:75], off
; __device__ __forceinline__ float siluf_(float x) { return x * __builtin_amdgcn_rcpf(1.f + __expf(-x)); }
; __device__ __forceinline__ u32x2 pack4(f32x4 v) { u32x2 r; r.x = cvt_pk_bf16(v[0], v[1]); r.y = cvt_pk_bf16(v[2], v[3]); return r; }
;     __device__ __forceinline__ void operator()(const f32x4 (&acc)[2][2][4][2], const pg8::Unit& u, int wr, int wc, int fr, int fq) const {
;     ...
;                 for (int n = 0; n < 2; ++n) {
;                     const int ch0 = chb + 4 * n;
;                     const f32x4 av = acc[ai][0][m][n] * rs[m], uv = acc[ai][1][m][n] * rs[m];
;                     f32x4 r1, r2;
; #pragma unroll
;                     for (int j = 0; j < 4; ++j) { r1[j] = __shfl(av[j], src1); r2[j] = __shfl(av[j], src2); }
;                     const f32x4 a1 = fr >= 1 ? r1 : p1[n], a2 = fr >= 2 ? r2 : p2[n];
;                     p1[n] = r1; p2[n] = r2;
;                     const f32x4 c = bb[n] + w0[n] * a2 + w1[n] * a1 + w2[n] * av;
;                     f32x4 g;
; #pragma unroll
;                     for (int j = 0; j < 4; ++j) g[j] = siluf_(c[j]) * uv[j];
;                     gp[n] = pack4(g);
;                     if (m == 3 && fr >= 14) *(f32x4*)(halo + ((size_t)blk * 6 + (fr - 14)) * DFF + ch0) = av;
;                     if (m == 0 && fr < 2) { *(f32x4*)(halo + ((size_t)blk * 6 + 2 + fr) * DFF + ch0) = av; *(f32x4*)(halo + ((size_t)blk * 6 + 4 + fr) * DFF + ch0) = uv; }
.LBB0_327:
	s_or_b64 exec, exec, s[84:85]
	v_mov_b32_e32 v99, v98
	v_mov_b32_e32 v122, v98
	v_mov_b32_e32 v123, v98
	v_pk_mul_f32 v[70:71], v[70:71], v[122:123]
	v_pk_mul_f32 v[68:69], v[68:69], v[98:99]
	s_nop 1
	v_mov_b32_dpp v104, v68 row_ror:1 row_mask:0xf bank_mask:0xf
	v_mov_b32_dpp v97, v68 row_ror:2 row_mask:0xf bank_mask:0xf
	v_mov_b32_dpp v107, v69 row_ror:1 row_mask:0xf bank_mask:0xf
	v_mov_b32_dpp v106, v69 row_ror:2 row_mask:0xf bank_mask:0xf
	v_mov_b32_dpp v109, v70 row_ror:1 row_mask:0xf bank_mask:0xf
	v_mov_b32_dpp v105, v70 row_ror:2 row_mask:0xf bank_mask:0xf
	v_mov_b32_dpp v110, v71 row_ror:1 row_mask:0xf bank_mask:0xf
	v_mov_b32_dpp v108, v71 row_ror:2 row_mask:0xf bank_mask:0xf
	v_pk_mul_f32 v[62:63], v[62:63], v[122:123]
	v_pk_mul_f32 v[60:61], v[60:61], v[98:99]
	s_and_saveexec_b64 s[84:85], s[44:45]
	s_cbranch_execz .LBB0_329
	global_store_dwordx4 v[102:103], v[68:71], off offset:16
	global_store_dwordx4 v[100:101], v[60:63], off offset:16

; __device__ __forceinline__ float siluf_(float x) { return x * __builtin_amdgcn_rcpf(1.f + __expf(-x)); }
; __device__ __forceinline__ u32x2 pack4(f32x4 v) { u32x2 r; r.x = cvt_pk_bf16(v[0], v[1]); r.y = cvt_pk_bf16(v[2], v[3]); return r; }
;     __device__ __forceinline__ void operator()(const f32x4 (&acc)[2][2][4][2], const pg8::Unit& u, int wr, int wc, int fr, int fq) const {
;     ...
;             for (int m = 0; m < 4; ++m) rs[m] = rsqrtf(ssq[blk * 64 + m * 16 + fr] * (1.f / DM) + EPS);
;             f32x4 p1[2] = {{0.f, 0.f, 0.f, 0.f}, {0.f, 0.f, 0.f, 0.f}}, p2[2] = {{0.f, 0.f, 0.f, 0.f}, {0.f, 0.f, 0.f, 0.f}};
; #pragma unroll
;             for (int m = 0; m < 4; ++m) {
;                 u32x2 gp[2];
; #pragma unroll
;                 for (int n = 0; n < 2; ++n) {
;                     const int ch0 = chb + 4 * n;
;                     const f32x4 av = acc[ai][0][m][n] * rs[m], uv = acc[ai][1][m][n] * rs[m];
;                     f32x4 r1, r2;
; #pragma unroll
;                     for (int j = 0; j < 4; ++j) { r1[j] = __shfl(av[j], src1); r2[j] = __shfl(av[j], src2); }
;                     const f32x4 a1 = fr >= 1 ? r1 : p1[n], a2 = fr >= 2 ? r2 : p2[n];
;                     p1[n] = r1; p2[n] = r2;
;                     const f32x4 c = bb[n] + w0[n] * a2 + w1[n] * a1 + w2[n] * av;
;                     f32x4 g;
; #pragma unroll
;                     for (int j = 0; j < 4; ++j) g[j] = siluf_(c[j]) * uv[j];
;                     gp[n] = pack4(g);
.LBB0_331:
	s_or_b64 exec, exec, s[84:85]
	v_fmamk_f32 v60, v121, 0x3a000000, v203
	v_cmp_gt_f32_e32 vcc, s71, v60
	v_mul_f32_e32 v61, 0x4b800000, v60
	s_mul_hi_i32 s49, s80, 6
	v_cndmask_b32_e32 v60, v60, v61, vcc
	v_rsq_f32_e32 v60, v60
	s_mul_i32 s48, s80, 6
	v_lshl_add_u64 v[72:73], s[48:49], 0, v[166:167]
	v_or_b32_e32 v69, 16, v96
	v_mul_f32_e32 v61, 0x45800000, v60
	v_cndmask_b32_e32 v70, v60, v61, vcc
	v_fmamk_f32 v60, v119, 0x3a000000, v203
	v_cmp_gt_f32_e32 vcc, s71, v60
	v_mul_f32_e32 v62, 0x4b800000, v60
	v_pk_mul_f32 v[44:45], v[44:45], v[70:71] op_sel_hi:[1,0]
	v_cndmask_b32_e32 v60, v60, v62, vcc
	v_rsq_f32_e32 v60, v60
	s_nop 1
	v_mov_b32_dpp v99, v44 row_ror:2 row_mask:0xf bank_mask:0xf
	v_mov_b32_dpp v101, v45 row_ror:2 row_mask:0xf bank_mask:0xf
	v_mov_b32_dpp v98, v44 row_ror:1 row_mask:0xf bank_mask:0xf
	v_mul_f32_e32 v62, 0x45800000, v60
	s_nop 1
	v_mov_b32_dpp v100, v45 row_ror:1 row_mask:0xf bank_mask:0xf
	v_cndmask_b32_e32 v68, v60, v62, vcc
	v_fmamk_f32 v60, v111, 0x3a000000, v203
	v_cmp_gt_f32_e32 vcc, s71, v60
	v_mul_f32_e32 v62, 0x4b800000, v60
	s_waitcnt lgkmcnt(2)
	v_cndmask_b32_e64 v81, v115, v101, s[40:41]
	v_cndmask_b32_e32 v60, v60, v62, vcc
	v_rsq_f32_e32 v60, v60
	v_cndmask_b32_e64 v80, v112, v99, s[40:41]
	v_pk_mul_f32 v[46:47], v[46:47], v[70:71] op_sel_hi:[1,0]
	s_waitcnt lgkmcnt(0)
	v_cndmask_b32_e64 v75, v100, v116, s[38:39]
	v_cndmask_b32_e64 v74, v98, v113, s[38:39]
	v_pk_fma_f32 v[80:81], v[88:89], v[80:81], v[92:93]
	s_nop 1
	v_mov_b32_dpp v103, v46 row_ror:2 row_mask:0xf bank_mask:0xf
	v_mov_b32_dpp v119, v47 row_ror:2 row_mask:0xf bank_mask:0xf
	v_pk_fma_f32 v[74:75], v[84:85], v[74:75], v[80:81]
	s_nop 1
	v_mov_b32_dpp v102, v46 row_ror:1 row_mask:0xf bank_mask:0xf
	v_mov_b32_dpp v111, v47 row_ror:1 row_mask:0xf bank_mask:0xf
	v_pk_fma_f32 v[44:45], v[76:77], v[44:45], v[74:75]
	v_mul_f32_e32 v62, 0x45800000, v60
	v_pk_mul_f32 v[42:43], v[42:43], v[70:71] op_sel_hi:[1,0]
	v_pk_mul_f32 v[40:41], v[40:41], v[70:71] op_sel_hi:[1,0]
	v_mul_f32_e32 v71, 0xbfb8aa3b, v44
	v_cndmask_b32_e32 v60, v60, v62, vcc
	v_mad_u64_u32 v[62:63], s[48:49], v72, s81, 0
	v_exp_f32_e32 v71, v71
	v_mov_b32_e32 v72, v63
	v_mad_u64_u32 v[72:73], s[48:49], v73, s81, v[72:73]
	s_waitcnt lgkmcnt(2)
	v_cndmask_b32_e64 v83, v117, v119, s[40:41]
	v_cndmask_b32_e64 v82, v114, v103, s[40:41]
	v_mov_b32_e32 v63, v72
	s_waitcnt lgkmcnt(0)
	v_cndmask_b32_e64 v73, v111, v120, s[38:39]
	v_cndmask_b32_e64 v72, v102, v118, s[38:39]
	v_pk_fma_f32 v[82:83], v[90:91], v[82:83], v[94:95]
	v_add_f32_e32 v71, 1.0, v71
	v_pk_fma_f32 v[72:73], v[86:87], v[72:73], v[82:83]
	v_pk_mul_f32 v[24:25], v[24:25], v[68:69] op_sel_hi:[1,0]
	v_pk_fma_f32 v[46:47], v[78:79], v[46:47], v[72:73]
	v_rcp_f32_e32 v72, v71
	v_mul_f32_e32 v71, 0xbfb8aa3b, v45
	v_exp_f32_e32 v71, v71
	v_pk_mul_f32 v[26:27], v[26:27], v[68:69] op_sel_hi:[1,0]
	v_pk_mul_f32 v[18:19], v[18:19], v[68:69] op_sel_hi:[1,0]
	v_pk_mul_f32 v[16:17], v[16:17], v[68:69] op_sel_hi:[1,0]
	v_add_f32_e32 v71, 1.0, v71
	v_rcp_f32_e32 v73, v71
	v_pk_mul_f32 v[36:37], v[36:37], v[70:71] op_sel_hi:[1,0]
	v_pk_mul_f32 v[38:39], v[38:39], v[70:71] op_sel_hi:[1,0]
	s_nop 1
	v_mov_b32_dpp v75, v37 row_ror:2 row_mask:0xf bank_mask:0xf
	v_pk_mul_f32 v[44:45], v[44:45], v[72:73]
	s_nop 1
	v_mov_b32_dpp v73, v36 row_ror:2 row_mask:0xf bank_mask:0xf
	v_pk_mul_f32 v[40:41], v[40:41], v[44:45]
	v_mul_f32_e32 v44, 0xbfb8aa3b, v46
	v_mul_f32_e32 v45, 0xbfb8aa3b, v47
	v_exp_f32_e32 v44, v44
	v_exp_f32_e32 v45, v45
	s_nop 1
	v_mov_b32_dpp v72, v36 row_ror:1 row_mask:0xf bank_mask:0xf
	v_mov_b32_dpp v74, v37 row_ror:1 row_mask:0xf bank_mask:0xf
	v_add_f32_e32 v44, 1.0, v44
	v_add_f32_e32 v45, 1.0, v45
	v_rcp_f32_e32 v44, v44
	v_rcp_f32_e32 v45, v45
	s_nop 1
	v_mov_b32_dpp v81, v38 row_ror:2 row_mask:0xf bank_mask:0xf
	v_mov_b32_dpp v83, v39 row_ror:2 row_mask:0xf bank_mask:0xf
	v_mov_b32_dpp v80, v38 row_ror:1 row_mask:0xf bank_mask:0xf
	v_mov_b32_dpp v82, v39 row_ror:1 row_mask:0xf bank_mask:0xf
	v_pk_mul_f32 v[44:45], v[46:47], v[44:45]
	s_waitcnt lgkmcnt(7)
	v_cndmask_b32_e64 v47, v106, v75, s[40:41]
	s_waitcnt lgkmcnt(6)
	v_cndmask_b32_e64 v46, v97, v73, s[40:41]
	v_pk_mul_f32 v[42:43], v[42:43], v[44:45]
	v_pk_mul_f32 v[34:35], v[34:35], v[70:71] op_sel_hi:[1,0]
	v_pk_mul_f32 v[32:33], v[32:33], v[70:71] op_sel_hi:[1,0]
	s_waitcnt lgkmcnt(4)
	v_cndmask_b32_e64 v45, v74, v107, s[38:39]
	v_cndmask_b32_e64 v44, v72, v104, s[38:39]
	s_waitcnt lgkmcnt(2)
	v_cndmask_b32_e64 v71, v108, v83, s[40:41]
	v_cndmask_b32_e64 v70, v105, v81, s[40:41]
	v_pk_fma_f32 v[46:47], v[56:57], v[46:47], v[64:65]
	v_cvt_pk_bf16_f32 v40, v40, v41
	v_cvt_pk_bf16_f32 v41, v42, v43
	s_waitcnt lgkmcnt(0)
; __device__ __forceinline__ float siluf_(float x) { return x * __builtin_amdgcn_rcpf(1.f + __expf(-x)); }
; __device__ __forceinline__ u32x2 pack4(f32x4 v) { u32x2 r; r.x = cvt_pk_bf16(v[0], v[1]); r.y = cvt_pk_bf16(v[2], v[3]); return r; }
;     __device__ __forceinline__ void operator()(const f32x4 (&acc)[2][2][4][2], const pg8::Unit& u, int wr, int wc, int fr, int fq) const {
;     ...
;             for (int m = 0; m < 4; ++m) {
;                 u32x2 gp[2];
; #pragma unroll
;                 for (int n = 0; n < 2; ++n) {
;                     const int ch0 = chb + 4 * n;
;                     const f32x4 av = acc[ai][0][m][n] * rs[m], uv = acc[ai][1][m][n] * rs[m];
;                     f32x4 r1, r2;
; #pragma unroll
;                     for (int j = 0; j < 4; ++j) { r1[j] = __shfl(av[j], src1); r2[j] = __shfl(av[j], src2); }
;                     const f32x4 a1 = fr >= 1 ? r1 : p1[n], a2 = fr >= 2 ? r2 : p2[n];
;                     p1[n] = r1; p2[n] = r2;
;                     const f32x4 c = bb[n] + w0[n] * a2 + w1[n] * a1 + w2[n] * av;
;                     f32x4 g;
; #pragma unroll
;                     for (int j = 0; j < 4; ++j) g[j] = siluf_(c[j]) * uv[j];
;                     gp[n] = pack4(g);
;                     if (m == 3 && fr >= 14) *(f32x4*)(halo + ((size_t)blk * 6 + (fr - 14)) * DFF + ch0) = av;
;                     if (m == 0 && fr < 2) { *(f32x4*)(halo + ((size_t)blk * 6 + 2 + fr) * DFF + ch0) = av; *(f32x4*)(halo + ((size_t)blk * 6 + 4 + fr) * DFF + ch0) = uv; }
;                 }
;                 const int row = blk * 64 + m * 16 + fr;
;                 if (m > 0 || fr >= 2) { const u32x4 gw = {gp[0].x, gp[0].y, gp[1].x, gp[1].y}; *(u32x4*)(G + (size_t)row * DFF + chb) = gw; }
	v_cndmask_b32_e64 v43, v82, v110, s[38:39]
	v_cndmask_b32_e64 v42, v80, v109, s[38:39]
	v_pk_fma_f32 v[70:71], v[58:59], v[70:71], v[66:67]
	v_pk_fma_f32 v[44:45], v[52:53], v[44:45], v[46:47]
	v_pk_fma_f32 v[42:43], v[54:55], v[42:43], v[70:71]
	v_pk_fma_f32 v[36:37], v[48:49], v[36:37], v[44:45]
	v_pk_fma_f32 v[38:39], v[50:51], v[38:39], v[42:43]
	v_mul_f32_e32 v42, 0xbfb8aa3b, v36
	v_mul_f32_e32 v43, 0xbfb8aa3b, v37
	v_exp_f32_e32 v42, v42
	v_exp_f32_e32 v43, v43
	v_or_b32_e32 v61, 32, v96
	v_pk_mul_f32 v[14:15], v[14:15], v[60:61] op_sel_hi:[1,0]
	v_add_f32_e32 v42, 1.0, v42
	v_add_f32_e32 v43, 1.0, v43
	v_rcp_f32_e32 v42, v42
	v_rcp_f32_e32 v43, v43
	v_pk_mul_f32 v[12:13], v[12:13], v[60:61] op_sel_hi:[1,0]
	v_pk_mul_f32 v[36:37], v[36:37], v[42:43]
	s_nop 0
	v_pk_mul_f32 v[32:33], v[32:33], v[36:37]
	v_mul_f32_e32 v36, 0xbfb8aa3b, v38
	v_mul_f32_e32 v37, 0xbfb8aa3b, v39
	v_exp_f32_e32 v36, v36
	v_exp_f32_e32 v37, v37
	v_cvt_pk_bf16_f32 v42, v32, v33
	v_mov_b64_e32 v[32:33], s[14:15]
	v_add_f32_e32 v36, 1.0, v36
	v_add_f32_e32 v37, 1.0, v37
	v_rcp_f32_e32 v36, v36
	v_rcp_f32_e32 v37, v37
	s_nop 0
	v_pk_mul_f32 v[36:37], v[38:39], v[36:37]
	s_nop 0
	v_pk_mul_f32 v[34:35], v[34:35], v[36:37]
	v_pk_mul_f32 v[38:39], v[30:31], v[68:69] op_sel_hi:[1,0]
	v_cvt_pk_bf16_f32 v43, v34, v35
	v_mad_i64_i32 v[34:35], s[48:49], v69, s86, v[32:33]
	v_lshl_add_u64 v[34:35], v[34:35], 0, v[128:129]
	global_store_dwordx4 v[34:35], v[40:43], off
	s_nop 1
	v_mov_b32_dpp v30, v38 row_ror:2 row_mask:0xf bank_mask:0xf
	v_mov_b32_dpp v37, v39 row_ror:2 row_mask:0xf bank_mask:0xf
	v_pk_mul_f32 v[40:41], v[28:29], v[68:69] op_sel_hi:[1,0]
	s_nop 1
	v_mov_b32_dpp v28, v40 row_ror:2 row_mask:0xf bank_mask:0xf
	v_mov_b32_dpp v31, v41 row_ror:2 row_mask:0xf bank_mask:0xf
	v_mov_b32_dpp v29, v40 row_ror:1 row_mask:0xf bank_mask:0xf
	v_mov_b32_dpp v34, v41 row_ror:1 row_mask:0xf bank_mask:0xf
	v_mov_b32_dpp v35, v38 row_ror:1 row_mask:0xf bank_mask:0xf
	v_mov_b32_dpp v36, v39 row_ror:1 row_mask:0xf bank_mask:0xf
	s_waitcnt lgkmcnt(4)
	v_cndmask_b32_e64 v47, v101, v31, s[40:41]
	v_cndmask_b32_e64 v46, v99, v28, s[40:41]
	s_waitcnt lgkmcnt(2)
	v_cndmask_b32_e64 v45, v34, v100, s[38:39]
	v_cndmask_b32_e64 v44, v29, v98, s[38:39]
	v_cndmask_b32_e64 v71, v119, v37, s[40:41]
	v_cndmask_b32_e64 v70, v103, v30, s[40:41]
	v_pk_fma_f32 v[46:47], v[88:89], v[46:47], v[92:93]
	s_waitcnt lgkmcnt(0)
	v_cndmask_b32_e64 v43, v36, v111, s[38:39]
	v_cndmask_b32_e64 v42, v35, v102, s[38:39]
	v_pk_fma_f32 v[70:71], v[90:91], v[70:71], v[94:95]
	v_pk_fma_f32 v[44:45], v[84:85], v[44:45], v[46:47]
	v_pk_fma_f32 v[42:43], v[86:87], v[42:43], v[70:71]
	v_pk_fma_f32 v[40:41], v[76:77], v[40:41], v[44:45]
	v_pk_fma_f32 v[38:39], v[78:79], v[38:39], v[42:43]
	v_mul_f32_e32 v42, 0xbfb8aa3b, v40
	v_mul_f32_e32 v43, 0xbfb8aa3b, v41
	v_exp_f32_e32 v42, v42
	v_exp_f32_e32 v43, v43
	v_add_f32_e32 v42, 1.0, v42
	v_add_f32_e32 v43, 1.0, v43
	v_rcp_f32_e32 v42, v42
	v_rcp_f32_e32 v43, v43
	s_nop 0
	v_pk_mul_f32 v[40:41], v[40:41], v[42:43]
	s_nop 0
	v_pk_mul_f32 v[24:25], v[24:25], v[40:41]
	v_mul_f32_e32 v40, 0xbfb8aa3b, v38
	v_mul_f32_e32 v41, 0xbfb8aa3b, v39
	v_exp_f32_e32 v40, v40
	v_exp_f32_e32 v41, v41
	v_pk_mul_f32 v[42:43], v[20:21], v[68:69] op_sel_hi:[1,0]
	s_nop 1
	v_mov_b32_dpp v20, v42 row_ror:2 row_mask:0xf bank_mask:0xf
	v_add_f32_e32 v40, 1.0, v40
	v_add_f32_e32 v41, 1.0, v41
	v_rcp_f32_e32 v40, v40
	v_rcp_f32_e32 v41, v41
	s_nop 1
	v_mov_b32_dpp v21, v42 row_ror:1 row_mask:0xf bank_mask:0xf
	v_pk_mul_f32 v[38:39], v[38:39], v[40:41]
	s_nop 0
	v_pk_mul_f32 v[26:27], v[26:27], v[38:39]
	v_pk_mul_f32 v[40:41], v[22:23], v[68:69] op_sel_hi:[1,0]
	s_nop 1
	v_mov_b32_dpp v23, v43 row_ror:2 row_mask:0xf bank_mask:0xf
	v_cvt_pk_bf16_f32 v38, v24, v25
	v_cvt_pk_bf16_f32 v39, v26, v27
	s_nop 1
	v_mov_b32_dpp v24, v43 row_ror:1 row_mask:0xf bank_mask:0xf
	v_mov_b32_dpp v22, v40 row_ror:2 row_mask:0xf bank_mask:0xf
	v_mov_b32_dpp v27, v41 row_ror:2 row_mask:0xf bank_mask:0xf
	v_mov_b32_dpp v25, v40 row_ror:1 row_mask:0xf bank_mask:0xf
	v_mov_b32_dpp v26, v41 row_ror:1 row_mask:0xf bank_mask:0xf
	s_waitcnt lgkmcnt(5)
	v_cndmask_b32_e64 v69, v75, v23, s[40:41]
	v_cndmask_b32_e64 v68, v73, v20, s[40:41]
	s_waitcnt lgkmcnt(4)
	v_cndmask_b32_e64 v47, v24, v74, s[38:39]
	v_cndmask_b32_e64 v46, v21, v72, s[38:39]
	s_waitcnt lgkmcnt(2)
	v_cndmask_b32_e64 v71, v83, v27, s[40:41]
	v_cndmask_b32_e64 v70, v81, v22, s[40:41]
	v_pk_fma_f32 v[68:69], v[56:57], v[68:69], v[64:65]
	s_waitcnt lgkmcnt(0)
	v_cndmask_b32_e64 v45, v26, v82, s[38:39]
	v_cndmask_b32_e64 v44, v25, v80, s[38:39]
	v_pk_fma_f32 v[70:71], v[58:59], v[70:71], v[66:67]
	v_pk_fma_f32 v[46:47], v[52:53], v[46:47], v[68:69]
	v_pk_fma_f32 v[44:45], v[54:55], v[44:45], v[70:71]
	v_pk_fma_f32 v[42:43], v[48:49], v[42:43], v[46:47]
	v_pk_fma_f32 v[40:41], v[50:51], v[40:41], v[44:45]
	v_mul_f32_e32 v44, 0xbfb8aa3b, v42
	v_mul_f32_e32 v45, 0xbfb8aa3b, v43
	v_exp_f32_e32 v44, v44
	v_exp_f32_e32 v45, v45
	s_nop 1
	v_mov_b32_dpp v68, v13 row_ror:1 row_mask:0xf bank_mask:0xf
	v_mov_b32_dpp v47, v13 row_ror:2 row_mask:0xf bank_mask:0xf
	v_add_f32_e32 v44, 1.0, v44
	v_add_f32_e32 v45, 1.0, v45
	v_rcp_f32_e32 v44, v44
	v_rcp_f32_e32 v45, v45
	s_nop 1
	v_mov_b32_dpp v70, v14 row_ror:1 row_mask:0xf bank_mask:0xf
	v_mov_b32_dpp v46, v14 row_ror:2 row_mask:0xf bank_mask:0xf
	v_mov_b32_dpp v71, v15 row_ror:1 row_mask:0xf bank_mask:0xf
	v_pk_mul_f32 v[42:43], v[42:43], v[44:45]
	s_nop 1
	v_mov_b32_dpp v45, v12 row_ror:1 row_mask:0xf bank_mask:0xf
	v_pk_mul_f32 v[16:17], v[16:17], v[42:43]
	v_mul_f32_e32 v42, 0xbfb8aa3b, v40
	v_mul_f32_e32 v43, 0xbfb8aa3b, v41
	v_exp_f32_e32 v42, v42
	v_exp_f32_e32 v43, v43
	s_nop 1
	v_mov_b32_dpp v44, v12 row_ror:2 row_mask:0xf bank_mask:0xf
	v_mov_b32_dpp v69, v15 row_ror:2 row_mask:0xf bank_mask:0xf
	v_add_f32_e32 v42, 1.0, v42
	v_add_f32_e32 v43, 1.0, v43
	v_rcp_f32_e32 v42, v42
	v_rcp_f32_e32 v43, v43
	s_nop 0
	v_pk_mul_f32 v[40:41], v[40:41], v[42:43]
	s_nop 0
	v_pk_mul_f32 v[18:19], v[18:19], v[40:41]
	v_cvt_pk_bf16_f32 v40, v16, v17
	v_mad_i64_i32 v[16:17], s[48:49], v61, s86, v[32:33]
	v_cvt_pk_bf16_f32 v41, v18, v19
	v_lshl_add_u64 v[16:17], v[16:17], 0, v[128:129]
	global_store_dwordx4 v[16:17], v[38:41], off
	v_lshl_add_u64 v[16:17], s[28:29], 0, v[62:63]
	v_lshl_add_u64 v[18:19], v[176:177], 2, v[16:17]
	s_and_saveexec_b64 s[84:85], s[42:43]
	s_cbranch_execz .LBB0_333
	global_store_dwordx4 v[18:19], v[12:15], off
; __device__ __forceinline__ float siluf_(float x) { return x * __builtin_amdgcn_rcpf(1.f + __expf(-x)); }
; __device__ __forceinline__ u32x2 pack4(f32x4 v) { u32x2 r; r.x = cvt_pk_bf16(v[0], v[1]); r.y = cvt_pk_bf16(v[2], v[3]); return r; }
;     __device__ __forceinline__ void operator()(const f32x4 (&acc)[2][2][4][2], const pg8::Unit& u, int wr, int wc, int fr, int fq) const {
;     ...
;                 for (int n = 0; n < 2; ++n) {
;                     const int ch0 = chb + 4 * n;
;                     const f32x4 av = acc[ai][0][m][n] * rs[m], uv = acc[ai][1][m][n] * rs[m];
;                     f32x4 r1, r2;
; #pragma unroll
;                     for (int j = 0; j < 4; ++j) { r1[j] = __shfl(av[j], src1); r2[j] = __shfl(av[j], src2); }
;                     const f32x4 a1 = fr >= 1 ? r1 : p1[n], a2 = fr >= 2 ? r2 : p2[n];
;                     p1[n] = r1; p2[n] = r2;
;                     const f32x4 c = bb[n] + w0[n] * a2 + w1[n] * a1 + w2[n] * av;
;                     f32x4 g;
; #pragma unroll
;                     for (int j = 0; j < 4; ++j) g[j] = siluf_(c[j]) * uv[j];
;                     gp[n] = pack4(g);
;                     if (m == 3 && fr >= 14) *(f32x4*)(halo + ((size_t)blk * 6 + (fr - 14)) * DFF + ch0) = av;
;                     if (m == 0 && fr < 2) { *(f32x4*)(halo + ((size_t)blk * 6 + 2 + fr) * DFF + ch0) = av; *(f32x4*)(halo + ((size_t)blk * 6 + 4 + fr) * DFF + ch0) = uv; }
.LBB0_333:
	s_or_b64 exec, exec, s[84:85]
	v_mov_b32_e32 v61, v60
	v_mov_b32_e32 v16, v60
	v_mov_b32_e32 v17, v60
	v_pk_mul_f32 v[10:11], v[10:11], v[16:17]
	v_pk_mul_f32 v[8:9], v[8:9], v[60:61]
	s_nop 1
	v_mov_b32_dpp v33, v8 row_ror:1 row_mask:0xf bank_mask:0xf
	v_mov_b32_dpp v32, v8 row_ror:2 row_mask:0xf bank_mask:0xf
	v_mov_b32_dpp v40, v9 row_ror:1 row_mask:0xf bank_mask:0xf
	v_mov_b32_dpp v39, v9 row_ror:2 row_mask:0xf bank_mask:0xf
	v_mov_b32_dpp v42, v10 row_ror:1 row_mask:0xf bank_mask:0xf
	v_mov_b32_dpp v38, v10 row_ror:2 row_mask:0xf bank_mask:0xf
	v_mov_b32_dpp v43, v11 row_ror:1 row_mask:0xf bank_mask:0xf
	v_mov_b32_dpp v41, v11 row_ror:2 row_mask:0xf bank_mask:0xf
	s_and_saveexec_b64 s[84:85], s[42:43]
	s_cbranch_execz .LBB0_335
	global_store_dwordx4 v[18:19], v[8:11], off offset:16
